# F4 + all GEMM K-loops: two LDS-DMA pieces moved from load segment 2 to segment 3 (2/4/4/6 per segment) + static priority raise for waves 0-3 with per-phase flips deleted
# speedup vs baseline: 1.0047x; 1.0047x over previous
.LBB1_224:
	s_add_u32 s60, s40, 0xfff80080
	s_addc_u32 s61, s41, -1
	s_add_i32 s78, 0, 0x10000
	s_cmp_eq_u32 s77, 28
	s_cselect_b32 s63, s27, s61
	s_cselect_b32 s62, s39, s60
	v_add_u32_e32 v112, s78, v148
	s_cselect_b32 s61, s72, s76
	s_cselect_b32 s60, s74, s75
	s_add_i32 s80, 0, 0x14000
	ds_read_b128 v[142:145], v112
	ds_read_b128 v[150:153], v112 offset:1024
	ds_read_b128 v[154:157], v112 offset:2048
	ds_read_b128 v[158:161], v112 offset:3072
	v_add_u32_e32 v112, s80, v148
	ds_read_b128 v[162:165], v112
	ds_read_b128 v[166:169], v112 offset:1024
	ds_read_b128 v[170:173], v112 offset:2048
	ds_read_b128 v[174:177], v112 offset:3072
	v_lshl_add_u64 v[146:147], s[40:41], 0, v[138:139]
	s_add_i32 m0, s9, 0xc000
	ds_read_b128 v[178:181], v149
	ds_read_b128 v[182:185], v149 offset:1024
	ds_read_b128 v[186:189], v149 offset:2048
	ds_read_b128 v[190:193], v149 offset:3072
	ds_read_b128 v[206:209], v149 offset:4096
	ds_read_b128 v[210:213], v149 offset:5120
	ds_read_b128 v[234:237], v149 offset:6144
	ds_read_b128 v[238:241], v149 offset:7168
	global_load_lds_dwordx4 v[146:147], off
	v_lshl_add_u64 v[146:147], s[40:41], 0, v[140:141]
	s_add_i32 m0, s9, 0xe000
	s_nop 0
	global_load_lds_dwordx4 v[146:147], off
	s_waitcnt vmcnt(8)
	s_waitcnt lgkmcnt(0)
	s_barrier
	s_waitcnt lgkmcnt(0)
	v_mfma_f32_16x16x32_bf16 v[126:129], v[142:145], v[178:181], v[126:129]
	v_mfma_f32_16x16x32_bf16 v[122:125], v[154:157], v[178:181], v[122:125]
	v_mfma_f32_16x16x32_bf16 v[108:111], v[142:145], v[186:189], v[108:111]
	v_mfma_f32_16x16x32_bf16 v[104:107], v[154:157], v[186:189], v[104:107]
	v_mfma_f32_16x16x32_bf16 v[92:95], v[142:145], v[206:209], v[92:95]
	v_mfma_f32_16x16x32_bf16 v[88:91], v[154:157], v[206:209], v[88:91]
	v_mfma_f32_16x16x32_bf16 v[76:79], v[142:145], v[234:237], v[76:79]
	v_mfma_f32_16x16x32_bf16 v[72:75], v[154:157], v[234:237], v[72:75]
	v_mfma_f32_16x16x32_bf16 v[126:129], v[150:153], v[182:185], v[126:129]
	v_mfma_f32_16x16x32_bf16 v[122:125], v[158:161], v[182:185], v[122:125]
	v_mfma_f32_16x16x32_bf16 v[108:111], v[150:153], v[190:193], v[108:111]
	v_mfma_f32_16x16x32_bf16 v[104:107], v[158:161], v[190:193], v[104:107]
	v_mfma_f32_16x16x32_bf16 v[92:95], v[150:153], v[210:213], v[92:95]
	v_mfma_f32_16x16x32_bf16 v[88:91], v[158:161], v[210:213], v[88:91]
	v_mfma_f32_16x16x32_bf16 v[76:79], v[150:153], v[238:241], v[76:79]
	v_mfma_f32_16x16x32_bf16 v[72:75], v[158:161], v[238:241], v[72:75]
	v_mfma_f32_16x16x32_bf16 v[118:121], v[162:165], v[178:181], v[118:121]
	v_mfma_f32_16x16x32_bf16 v[114:117], v[170:173], v[178:181], v[114:117]
	v_mfma_f32_16x16x32_bf16 v[100:103], v[162:165], v[186:189], v[100:103]
	v_mfma_f32_16x16x32_bf16 v[96:99], v[170:173], v[186:189], v[96:99]
	v_mfma_f32_16x16x32_bf16 v[84:87], v[162:165], v[206:209], v[84:87]
	v_mfma_f32_16x16x32_bf16 v[80:83], v[170:173], v[206:209], v[80:83]
	v_mfma_f32_16x16x32_bf16 v[68:71], v[162:165], v[234:237], v[68:71]
	v_mfma_f32_16x16x32_bf16 v[64:67], v[170:173], v[234:237], v[64:67]
	v_mfma_f32_16x16x32_bf16 v[118:121], v[166:169], v[182:185], v[118:121]
	v_mfma_f32_16x16x32_bf16 v[114:117], v[174:177], v[182:185], v[114:117]
	v_mfma_f32_16x16x32_bf16 v[100:103], v[166:169], v[190:193], v[100:103]
	v_mfma_f32_16x16x32_bf16 v[96:99], v[174:177], v[190:193], v[96:99]
	v_mfma_f32_16x16x32_bf16 v[84:87], v[166:169], v[210:213], v[84:87]
	v_mfma_f32_16x16x32_bf16 v[80:83], v[174:177], v[210:213], v[80:83]
	v_mfma_f32_16x16x32_bf16 v[68:71], v[166:169], v[238:241], v[68:71]
	v_mfma_f32_16x16x32_bf16 v[64:67], v[174:177], v[238:241], v[64:67]
	s_barrier
	s_add_i32 s78, s78, s7
	v_lshl_add_u64 v[146:147], s[60:61], 0, v[132:133]
	s_mov_b32 m0, s78
	ds_read_b128 v[178:181], v149 offset:16384
	ds_read_b128 v[182:185], v149 offset:17408
	ds_read_b128 v[186:189], v149 offset:18432
	ds_read_b128 v[190:193], v149 offset:19456
	ds_read_b128 v[206:209], v149 offset:20480
	ds_read_b128 v[210:213], v149 offset:21504
	ds_read_b128 v[234:237], v149 offset:22528
	ds_read_b128 v[238:241], v149 offset:23552
	global_load_lds_dwordx4 v[146:147], off
	s_add_i32 m0, s78, 0x2000
	s_add_u32 s78, s60, 0x20000
	v_lshl_add_u64 v[198:199], s[60:61], 0, v[136:137]
	s_addc_u32 s79, s61, 0
	s_add_i32 s80, s80, s7
	global_load_lds_dwordx4 v[198:199], off
	v_lshl_add_u64 v[200:201], s[78:79], 0, v[132:133]
	s_mov_b32 m0, s80
	v_lshl_add_u64 v[242:243], s[62:63], 0, v[134:135]
	global_load_lds_dwordx4 v[200:201], off
	v_lshl_add_u64 v[200:201], s[78:79], 0, v[136:137]
	s_add_i32 m0, s80, 0x2000
	s_nop 0
	global_load_lds_dwordx4 v[200:201], off
	s_waitcnt vmcnt(6)
	s_waitcnt lgkmcnt(0)
	s_barrier
	s_waitcnt lgkmcnt(0)
	v_mfma_f32_16x16x32_bf16 v[60:63], v[142:145], v[178:181], v[60:63]
	v_mfma_f32_16x16x32_bf16 v[56:59], v[154:157], v[178:181], v[56:59]
	v_mfma_f32_16x16x32_bf16 v[44:47], v[142:145], v[186:189], v[44:47]
	v_mfma_f32_16x16x32_bf16 v[40:43], v[154:157], v[186:189], v[40:43]
	v_mfma_f32_16x16x32_bf16 v[28:31], v[142:145], v[206:209], v[28:31]
	v_mfma_f32_16x16x32_bf16 v[24:27], v[154:157], v[206:209], v[24:27]
	v_mfma_f32_16x16x32_bf16 v[12:15], v[142:145], v[234:237], v[12:15]
	v_mfma_f32_16x16x32_bf16 v[8:11], v[154:157], v[234:237], v[8:11]
	v_mfma_f32_16x16x32_bf16 v[60:63], v[150:153], v[182:185], v[60:63]
	v_mfma_f32_16x16x32_bf16 v[56:59], v[158:161], v[182:185], v[56:59]
	v_mfma_f32_16x16x32_bf16 v[44:47], v[150:153], v[190:193], v[44:47]
	v_mfma_f32_16x16x32_bf16 v[40:43], v[158:161], v[190:193], v[40:43]
	v_mfma_f32_16x16x32_bf16 v[28:31], v[150:153], v[210:213], v[28:31]
	v_mfma_f32_16x16x32_bf16 v[24:27], v[158:161], v[210:213], v[24:27]
	v_mfma_f32_16x16x32_bf16 v[12:15], v[150:153], v[238:241], v[12:15]
	v_mfma_f32_16x16x32_bf16 v[8:11], v[158:161], v[238:241], v[8:11]
	v_mfma_f32_16x16x32_bf16 v[52:55], v[162:165], v[178:181], v[52:55]
	v_mfma_f32_16x16x32_bf16 v[48:51], v[170:173], v[178:181], v[48:51]
	v_mfma_f32_16x16x32_bf16 v[36:39], v[162:165], v[186:189], v[36:39]
	v_mfma_f32_16x16x32_bf16 v[32:35], v[170:173], v[186:189], v[32:35]
	v_mfma_f32_16x16x32_bf16 v[20:23], v[162:165], v[206:209], v[20:23]
	v_mfma_f32_16x16x32_bf16 v[16:19], v[170:173], v[206:209], v[16:19]
	v_mfma_f32_16x16x32_bf16 v[4:7], v[162:165], v[234:237], v[4:7]
	v_mfma_f32_16x16x32_bf16 v[0:3], v[170:173], v[234:237], v[0:3]
	v_mfma_f32_16x16x32_bf16 v[52:55], v[166:169], v[182:185], v[52:55]
	v_mfma_f32_16x16x32_bf16 v[48:51], v[174:177], v[182:185], v[48:51]
	v_mfma_f32_16x16x32_bf16 v[36:39], v[166:169], v[190:193], v[36:39]
	v_mfma_f32_16x16x32_bf16 v[32:35], v[174:177], v[190:193], v[32:35]
	v_mfma_f32_16x16x32_bf16 v[20:23], v[166:169], v[210:213], v[20:23]
	v_mfma_f32_16x16x32_bf16 v[16:19], v[174:177], v[210:213], v[16:19]
	v_mfma_f32_16x16x32_bf16 v[4:7], v[166:169], v[238:241], v[4:7]
	v_mfma_f32_16x16x32_bf16 v[0:3], v[174:177], v[238:241], v[0:3]
	s_barrier
	s_add_i32 s78, 0, 0x18000
	v_add_u32_e32 v112, s78, v148
	s_add_i32 s79, 0, 0x1c000
	ds_read_b128 v[142:145], v112
	ds_read_b128 v[150:153], v112 offset:1024
	ds_read_b128 v[154:157], v112 offset:2048
	ds_read_b128 v[158:161], v112 offset:3072
	v_add_u32_e32 v112, s79, v148
	ds_read_b128 v[162:165], v112
	ds_read_b128 v[166:169], v112 offset:1024
	ds_read_b128 v[170:173], v112 offset:2048
	ds_read_b128 v[174:177], v112 offset:3072
	v_lshl_add_u64 v[200:201], s[62:63], 0, v[130:131]
	s_mov_b32 m0, s9
	s_nop 0
	global_load_lds_dwordx4 v[200:201], off
	s_mov_b32 m0, s10
	s_nop 0
	global_load_lds_dwordx4 v[242:243], off
	s_add_u32 s62, s62, 0x80000
	s_addc_u32 s63, s63, 0
	s_mov_b32 m0, s11
	v_lshl_add_u64 v[244:245], s[62:63], 0, v[130:131]
	ds_read_b128 v[178:181], v149 offset:32768
	ds_read_b128 v[182:185], v149 offset:33792
	ds_read_b128 v[186:189], v149 offset:34816
	ds_read_b128 v[190:193], v149 offset:35840
	ds_read_b128 v[206:209], v149 offset:36864
	ds_read_b128 v[210:213], v149 offset:37888
	ds_read_b128 v[234:237], v149 offset:38912
	ds_read_b128 v[238:241], v149 offset:39936
	global_load_lds_dwordx4 v[244:245], off
	v_lshl_add_u64 v[244:245], s[62:63], 0, v[134:135]
	s_mov_b32 m0, s24
	s_nop 0
	global_load_lds_dwordx4 v[244:245], off
	s_waitcnt vmcnt(8)
	s_waitcnt lgkmcnt(0)
	s_barrier
	s_waitcnt lgkmcnt(0)
	v_mfma_f32_16x16x32_bf16 v[126:129], v[142:145], v[178:181], v[126:129]
	v_mfma_f32_16x16x32_bf16 v[122:125], v[154:157], v[178:181], v[122:125]
	v_mfma_f32_16x16x32_bf16 v[108:111], v[142:145], v[186:189], v[108:111]
	v_mfma_f32_16x16x32_bf16 v[104:107], v[154:157], v[186:189], v[104:107]
	v_mfma_f32_16x16x32_bf16 v[92:95], v[142:145], v[206:209], v[92:95]
	v_mfma_f32_16x16x32_bf16 v[88:91], v[154:157], v[206:209], v[88:91]
	v_mfma_f32_16x16x32_bf16 v[76:79], v[142:145], v[234:237], v[76:79]
	v_mfma_f32_16x16x32_bf16 v[72:75], v[154:157], v[234:237], v[72:75]
	v_mfma_f32_16x16x32_bf16 v[126:129], v[150:153], v[182:185], v[126:129]
	v_mfma_f32_16x16x32_bf16 v[122:125], v[158:161], v[182:185], v[122:125]
	v_mfma_f32_16x16x32_bf16 v[108:111], v[150:153], v[190:193], v[108:111]
	v_mfma_f32_16x16x32_bf16 v[104:107], v[158:161], v[190:193], v[104:107]
	v_mfma_f32_16x16x32_bf16 v[92:95], v[150:153], v[210:213], v[92:95]
	v_mfma_f32_16x16x32_bf16 v[88:91], v[158:161], v[210:213], v[88:91]
	v_mfma_f32_16x16x32_bf16 v[76:79], v[150:153], v[238:241], v[76:79]
	v_mfma_f32_16x16x32_bf16 v[72:75], v[158:161], v[238:241], v[72:75]
	v_mfma_f32_16x16x32_bf16 v[118:121], v[162:165], v[178:181], v[118:121]
	v_mfma_f32_16x16x32_bf16 v[114:117], v[170:173], v[178:181], v[114:117]
	v_mfma_f32_16x16x32_bf16 v[100:103], v[162:165], v[186:189], v[100:103]
	v_mfma_f32_16x16x32_bf16 v[96:99], v[170:173], v[186:189], v[96:99]
	v_mfma_f32_16x16x32_bf16 v[84:87], v[162:165], v[206:209], v[84:87]
	v_mfma_f32_16x16x32_bf16 v[80:83], v[170:173], v[206:209], v[80:83]
	v_mfma_f32_16x16x32_bf16 v[68:71], v[162:165], v[234:237], v[68:71]
	v_mfma_f32_16x16x32_bf16 v[64:67], v[170:173], v[234:237], v[64:67]
	v_mfma_f32_16x16x32_bf16 v[118:121], v[166:169], v[182:185], v[118:121]
	v_mfma_f32_16x16x32_bf16 v[114:117], v[174:177], v[182:185], v[114:117]
	v_mfma_f32_16x16x32_bf16 v[100:103], v[166:169], v[190:193], v[100:103]
	v_mfma_f32_16x16x32_bf16 v[96:99], v[174:177], v[190:193], v[96:99]
	v_mfma_f32_16x16x32_bf16 v[84:87], v[166:169], v[210:213], v[84:87]
	v_mfma_f32_16x16x32_bf16 v[80:83], v[174:177], v[210:213], v[80:83]
	v_mfma_f32_16x16x32_bf16 v[68:71], v[166:169], v[238:241], v[68:71]
	v_mfma_f32_16x16x32_bf16 v[64:67], v[174:177], v[238:241], v[64:67]
	s_barrier
	s_add_i32 s62, s78, s7
	v_lshl_add_u64 v[146:147], v[146:147], 0, s[48:49]
	s_mov_b32 m0, s62
	ds_read_b128 v[178:181], v149 offset:49152
	ds_read_b128 v[182:185], v149 offset:50176
	ds_read_b128 v[186:189], v149 offset:51200
	ds_read_b128 v[190:193], v149 offset:52224
	ds_read_b128 v[206:209], v149 offset:53248
	ds_read_b128 v[210:213], v149 offset:54272
	ds_read_b128 v[234:237], v149 offset:55296
	ds_read_b128 v[238:241], v149 offset:56320
	global_load_lds_dwordx4 v[146:147], off
	s_add_i32 m0, s62, 0x2000
	s_add_u32 s60, s60, 0x20080
	v_lshl_add_u64 v[146:147], v[198:199], 0, s[48:49]
	s_addc_u32 s61, s61, 0
	s_add_i32 s62, s79, s7
	global_load_lds_dwordx4 v[146:147], off
	v_lshl_add_u64 v[146:147], s[60:61], 0, v[132:133]
	s_mov_b32 m0, s62
	s_nop 0
	global_load_lds_dwordx4 v[146:147], off
	v_lshl_add_u64 v[146:147], s[60:61], 0, v[136:137]
	s_add_i32 m0, s62, 0x2000
	s_nop 0
	global_load_lds_dwordx4 v[146:147], off
	v_lshl_add_u64 v[146:147], v[200:201], 0, s[48:49]
	s_mov_b32 m0, s54
	s_nop 0
	global_load_lds_dwordx4 v[146:147], off
	v_lshl_add_u64 v[146:147], v[242:243], 0, s[48:49]
	s_mov_b32 m0, s55
	s_nop 0
	global_load_lds_dwordx4 v[146:147], off
	s_waitcnt vmcnt(8)
	s_waitcnt lgkmcnt(0)
	s_barrier
	s_waitcnt lgkmcnt(0)
	v_mfma_f32_16x16x32_bf16 v[60:63], v[142:145], v[178:181], v[60:63]
	v_mfma_f32_16x16x32_bf16 v[56:59], v[154:157], v[178:181], v[56:59]
	v_mfma_f32_16x16x32_bf16 v[44:47], v[142:145], v[186:189], v[44:47]
	v_mfma_f32_16x16x32_bf16 v[40:43], v[154:157], v[186:189], v[40:43]
	v_mfma_f32_16x16x32_bf16 v[28:31], v[142:145], v[206:209], v[28:31]
	v_mfma_f32_16x16x32_bf16 v[24:27], v[154:157], v[206:209], v[24:27]
	v_mfma_f32_16x16x32_bf16 v[12:15], v[142:145], v[234:237], v[12:15]
	v_mfma_f32_16x16x32_bf16 v[8:11], v[154:157], v[234:237], v[8:11]
	v_mfma_f32_16x16x32_bf16 v[60:63], v[150:153], v[182:185], v[60:63]
	v_mfma_f32_16x16x32_bf16 v[56:59], v[158:161], v[182:185], v[56:59]
	v_mfma_f32_16x16x32_bf16 v[44:47], v[150:153], v[190:193], v[44:47]
	v_mfma_f32_16x16x32_bf16 v[40:43], v[158:161], v[190:193], v[40:43]
	v_mfma_f32_16x16x32_bf16 v[28:31], v[150:153], v[210:213], v[28:31]
	v_mfma_f32_16x16x32_bf16 v[24:27], v[158:161], v[210:213], v[24:27]
	v_mfma_f32_16x16x32_bf16 v[12:15], v[150:153], v[238:241], v[12:15]
	v_mfma_f32_16x16x32_bf16 v[8:11], v[158:161], v[238:241], v[8:11]
	v_mfma_f32_16x16x32_bf16 v[52:55], v[162:165], v[178:181], v[52:55]
	v_mfma_f32_16x16x32_bf16 v[48:51], v[170:173], v[178:181], v[48:51]
	v_mfma_f32_16x16x32_bf16 v[36:39], v[162:165], v[186:189], v[36:39]
	v_mfma_f32_16x16x32_bf16 v[32:35], v[170:173], v[186:189], v[32:35]
	v_mfma_f32_16x16x32_bf16 v[20:23], v[162:165], v[206:209], v[20:23]
	v_mfma_f32_16x16x32_bf16 v[16:19], v[170:173], v[206:209], v[16:19]
	v_mfma_f32_16x16x32_bf16 v[4:7], v[162:165], v[234:237], v[4:7]
	v_mfma_f32_16x16x32_bf16 v[0:3], v[170:173], v[234:237], v[0:3]
	v_mfma_f32_16x16x32_bf16 v[52:55], v[166:169], v[182:185], v[52:55]
	v_mfma_f32_16x16x32_bf16 v[48:51], v[174:177], v[182:185], v[48:51]
	v_mfma_f32_16x16x32_bf16 v[36:39], v[166:169], v[190:193], v[36:39]
	v_mfma_f32_16x16x32_bf16 v[32:35], v[174:177], v[190:193], v[32:35]
	v_mfma_f32_16x16x32_bf16 v[20:23], v[166:169], v[210:213], v[20:23]
	v_mfma_f32_16x16x32_bf16 v[16:19], v[174:177], v[210:213], v[16:19]
	v_mfma_f32_16x16x32_bf16 v[4:7], v[166:169], v[238:241], v[4:7]
	v_mfma_f32_16x16x32_bf16 v[0:3], v[174:177], v[238:241], v[0:3]
	s_barrier
	s_add_i32 s77, s77, 2
	s_add_u32 s40, s40, 0x100
	s_addc_u32 s41, s41, 0
	s_add_u32 s75, s75, 0x100
	s_addc_u32 s76, s76, 0
	s_cmp_gt_u32 s77, 29
	s_cbranch_scc0 .LBB1_224
	s_and_b64 vcc, exec, s[18:19]
	s_cbranch_vccz .LBB1_227
	s_barrier

.LBB1_621:
	s_add_u32 s5, s82, s84
	s_addc_u32 s6, s83, s85
	s_add_u32 s5, s5, 0x100
	s_addc_u32 s6, s6, 0
	s_add_u32 s7, s56, s84
	s_addc_u32 s9, s57, s85
	s_add_i32 s10, 0, 0x10000
	s_cmpk_eq_i32 s84, 0xf00
	s_cselect_b32 s19, s3, s6
	s_cselect_b32 s18, s24, s5
	v_add_u32_e32 v112, s10, v154
	s_cselect_b32 s17, s1, s9
	s_cselect_b32 s16, s45, s7
	s_add_i32 s5, 0, 0x14000
	ds_read_b128 v[148:151], v112
	ds_read_b128 v[156:159], v112 offset:1024
	ds_read_b128 v[160:163], v112 offset:2048
	ds_read_b128 v[164:167], v112 offset:3072
	v_add_u32_e32 v112, s5, v154
	ds_read_b128 v[168:171], v112
	ds_read_b128 v[172:175], v112 offset:1024
	ds_read_b128 v[176:179], v112 offset:2048
	ds_read_b128 v[180:183], v112 offset:3072
	v_lshl_add_u64 v[114:115], v[144:145], 0, s[84:85]
	s_add_i32 m0, s59, 0xc000
	ds_read_b128 v[184:187], v155
	ds_read_b128 v[188:191], v155 offset:1024
	ds_read_b128 v[198:201], v155 offset:2048
	ds_read_b128 v[206:209], v155 offset:3072
	ds_read_b128 v[210:213], v155 offset:4096
	ds_read_b128 v[234:237], v155 offset:5120
	ds_read_b128 v[238:241], v155 offset:6144
	ds_read_b128 v[242:245], v155 offset:7168
	global_load_lds_dwordx4 v[114:115], off
	v_lshl_add_u64 v[114:115], v[146:147], 0, s[84:85]
	s_add_i32 m0, s59, 0xe000
	s_nop 0
	global_load_lds_dwordx4 v[114:115], off
	s_waitcnt vmcnt(8)
	s_waitcnt lgkmcnt(0)
	s_barrier
	s_waitcnt lgkmcnt(0)
	v_mfma_f32_16x16x32_bf16 v[128:131], v[148:151], v[184:187], v[128:131]
	v_mfma_f32_16x16x32_bf16 v[124:127], v[160:163], v[184:187], v[124:127]
	v_mfma_f32_16x16x32_bf16 v[108:111], v[148:151], v[198:201], v[108:111]
	v_mfma_f32_16x16x32_bf16 v[104:107], v[160:163], v[198:201], v[104:107]
	v_mfma_f32_16x16x32_bf16 v[92:95], v[148:151], v[210:213], v[92:95]
	v_mfma_f32_16x16x32_bf16 v[88:91], v[160:163], v[210:213], v[88:91]
	v_mfma_f32_16x16x32_bf16 v[76:79], v[148:151], v[238:241], v[76:79]
	v_mfma_f32_16x16x32_bf16 v[72:75], v[160:163], v[238:241], v[72:75]
	v_mfma_f32_16x16x32_bf16 v[128:131], v[156:159], v[188:191], v[128:131]
	v_mfma_f32_16x16x32_bf16 v[124:127], v[164:167], v[188:191], v[124:127]
	v_mfma_f32_16x16x32_bf16 v[108:111], v[156:159], v[206:209], v[108:111]
	v_mfma_f32_16x16x32_bf16 v[104:107], v[164:167], v[206:209], v[104:107]
	v_mfma_f32_16x16x32_bf16 v[92:95], v[156:159], v[234:237], v[92:95]
	v_mfma_f32_16x16x32_bf16 v[88:91], v[164:167], v[234:237], v[88:91]
	v_mfma_f32_16x16x32_bf16 v[76:79], v[156:159], v[242:245], v[76:79]
	v_mfma_f32_16x16x32_bf16 v[72:75], v[164:167], v[242:245], v[72:75]
	v_mfma_f32_16x16x32_bf16 v[120:123], v[168:171], v[184:187], v[120:123]
	v_mfma_f32_16x16x32_bf16 v[114:117], v[176:179], v[184:187], v[116:119]
	v_mfma_f32_16x16x32_bf16 v[100:103], v[168:171], v[198:201], v[100:103]
	v_mfma_f32_16x16x32_bf16 v[96:99], v[176:179], v[198:201], v[96:99]
	v_mfma_f32_16x16x32_bf16 v[84:87], v[168:171], v[210:213], v[84:87]
	v_mfma_f32_16x16x32_bf16 v[80:83], v[176:179], v[210:213], v[80:83]
	v_mfma_f32_16x16x32_bf16 v[68:71], v[168:171], v[238:241], v[68:71]
	v_mfma_f32_16x16x32_bf16 v[64:67], v[176:179], v[238:241], v[64:67]
	v_mfma_f32_16x16x32_bf16 v[120:123], v[172:175], v[188:191], v[120:123]
	v_mfma_f32_16x16x32_bf16 v[114:117], v[180:183], v[188:191], v[114:117]
	v_mfma_f32_16x16x32_bf16 v[100:103], v[172:175], v[206:209], v[100:103]
	v_mfma_f32_16x16x32_bf16 v[96:99], v[180:183], v[206:209], v[96:99]
	v_mfma_f32_16x16x32_bf16 v[84:87], v[172:175], v[234:237], v[84:87]
	v_mfma_f32_16x16x32_bf16 v[80:83], v[180:183], v[234:237], v[80:83]
	v_mfma_f32_16x16x32_bf16 v[68:71], v[172:175], v[242:245], v[68:71]
	v_mfma_f32_16x16x32_bf16 v[64:67], v[180:183], v[242:245], v[64:67]
	s_barrier
	s_add_i32 s6, s10, s58
	v_lshl_add_u64 v[152:153], s[16:17], 0, v[134:135]
	s_mov_b32 m0, s6
	ds_read_b128 v[184:187], v155 offset:16384
	ds_read_b128 v[188:191], v155 offset:17408
	ds_read_b128 v[198:201], v155 offset:18432
	ds_read_b128 v[206:209], v155 offset:19456
	ds_read_b128 v[210:213], v155 offset:20480
	ds_read_b128 v[234:237], v155 offset:21504
	ds_read_b128 v[238:241], v155 offset:22528
	ds_read_b128 v[242:245], v155 offset:23552
	global_load_lds_dwordx4 v[152:153], off
	s_add_i32 m0, s6, 0x2000
	s_add_u32 s6, s16, 0x20000
	v_lshl_add_u64 v[192:193], s[16:17], 0, v[138:139]
	s_addc_u32 s7, s17, 0
	s_add_i32 s5, s5, s58
	global_load_lds_dwordx4 v[192:193], off
	v_lshl_add_u64 v[118:119], s[6:7], 0, v[134:135]
	s_mov_b32 m0, s5
	v_lshl_add_u64 v[246:247], s[18:19], 0, v[132:133]
	global_load_lds_dwordx4 v[118:119], off
	v_lshl_add_u64 v[118:119], s[6:7], 0, v[138:139]
	s_add_i32 m0, s5, 0x2000
	v_lshl_add_u64 v[248:249], s[18:19], 0, v[136:137]
	global_load_lds_dwordx4 v[118:119], off
	s_waitcnt vmcnt(6)
	s_waitcnt lgkmcnt(0)
	s_barrier
	s_waitcnt lgkmcnt(0)
	v_mfma_f32_16x16x32_bf16 v[60:63], v[148:151], v[184:187], v[60:63]
	v_mfma_f32_16x16x32_bf16 v[56:59], v[160:163], v[184:187], v[56:59]
	v_mfma_f32_16x16x32_bf16 v[44:47], v[148:151], v[198:201], v[44:47]
	v_mfma_f32_16x16x32_bf16 v[40:43], v[160:163], v[198:201], v[40:43]
	v_mfma_f32_16x16x32_bf16 v[28:31], v[148:151], v[210:213], v[28:31]
	v_mfma_f32_16x16x32_bf16 v[24:27], v[160:163], v[210:213], v[24:27]
	v_mfma_f32_16x16x32_bf16 v[12:15], v[148:151], v[238:241], v[12:15]
	v_mfma_f32_16x16x32_bf16 v[8:11], v[160:163], v[238:241], v[8:11]
	v_mfma_f32_16x16x32_bf16 v[60:63], v[156:159], v[188:191], v[60:63]
	v_mfma_f32_16x16x32_bf16 v[56:59], v[164:167], v[188:191], v[56:59]
	v_mfma_f32_16x16x32_bf16 v[44:47], v[156:159], v[206:209], v[44:47]
	v_mfma_f32_16x16x32_bf16 v[40:43], v[164:167], v[206:209], v[40:43]
	v_mfma_f32_16x16x32_bf16 v[28:31], v[156:159], v[234:237], v[28:31]
	v_mfma_f32_16x16x32_bf16 v[24:27], v[164:167], v[234:237], v[24:27]
	v_mfma_f32_16x16x32_bf16 v[12:15], v[156:159], v[242:245], v[12:15]
	v_mfma_f32_16x16x32_bf16 v[8:11], v[164:167], v[242:245], v[8:11]
	v_mfma_f32_16x16x32_bf16 v[52:55], v[168:171], v[184:187], v[52:55]
	v_mfma_f32_16x16x32_bf16 v[48:51], v[176:179], v[184:187], v[48:51]
	v_mfma_f32_16x16x32_bf16 v[36:39], v[168:171], v[198:201], v[36:39]
	v_mfma_f32_16x16x32_bf16 v[32:35], v[176:179], v[198:201], v[32:35]
	v_mfma_f32_16x16x32_bf16 v[20:23], v[168:171], v[210:213], v[20:23]
	v_mfma_f32_16x16x32_bf16 v[16:19], v[176:179], v[210:213], v[16:19]
	v_mfma_f32_16x16x32_bf16 v[4:7], v[168:171], v[238:241], v[4:7]
	v_mfma_f32_16x16x32_bf16 v[0:3], v[176:179], v[238:241], v[0:3]
	v_mfma_f32_16x16x32_bf16 v[52:55], v[172:175], v[188:191], v[52:55]
	v_mfma_f32_16x16x32_bf16 v[48:51], v[180:183], v[188:191], v[48:51]
	v_mfma_f32_16x16x32_bf16 v[36:39], v[172:175], v[206:209], v[36:39]
	v_mfma_f32_16x16x32_bf16 v[32:35], v[180:183], v[206:209], v[32:35]
	v_mfma_f32_16x16x32_bf16 v[20:23], v[172:175], v[234:237], v[20:23]
	v_mfma_f32_16x16x32_bf16 v[16:19], v[180:183], v[234:237], v[16:19]
	v_mfma_f32_16x16x32_bf16 v[4:7], v[172:175], v[242:245], v[4:7]
	v_mfma_f32_16x16x32_bf16 v[0:3], v[180:183], v[242:245], v[0:3]
	s_barrier
	s_add_i32 s5, 0, 0x18000
	v_add_u32_e32 v112, s5, v154
	s_add_i32 s9, 0, 0x1c000
	ds_read_b128 v[148:151], v112
	ds_read_b128 v[156:159], v112 offset:1024
	ds_read_b128 v[160:163], v112 offset:2048
	ds_read_b128 v[164:167], v112 offset:3072
	v_add_u32_e32 v112, s9, v154
	ds_read_b128 v[168:171], v112
	ds_read_b128 v[172:175], v112 offset:1024
	ds_read_b128 v[176:179], v112 offset:2048
	ds_read_b128 v[180:183], v112 offset:3072
	s_mov_b32 m0, s59
	s_nop 0
	global_load_lds_dwordx4 v[246:247], off
	s_mov_b32 m0, s60
	s_nop 0
	global_load_lds_dwordx4 v[248:249], off
	s_add_u32 s6, s18, 0x80000
	s_addc_u32 s7, s19, 0
	s_mov_b32 m0, s61
	v_lshl_add_u64 v[118:119], s[6:7], 0, v[132:133]
	ds_read_b128 v[184:187], v155 offset:32768
	ds_read_b128 v[188:191], v155 offset:33792
	ds_read_b128 v[198:201], v155 offset:34816
	ds_read_b128 v[206:209], v155 offset:35840
	ds_read_b128 v[210:213], v155 offset:36864
	ds_read_b128 v[234:237], v155 offset:37888
	ds_read_b128 v[238:241], v155 offset:38912
	ds_read_b128 v[242:245], v155 offset:39936
	global_load_lds_dwordx4 v[118:119], off
	v_lshl_add_u64 v[118:119], s[6:7], 0, v[136:137]
	s_mov_b32 m0, s62
	s_nop 0
	global_load_lds_dwordx4 v[118:119], off
	s_waitcnt vmcnt(8)
	s_waitcnt lgkmcnt(0)
	s_barrier
	s_waitcnt lgkmcnt(0)
	v_mfma_f32_16x16x32_bf16 v[128:131], v[148:151], v[184:187], v[128:131]
	v_mfma_f32_16x16x32_bf16 v[124:127], v[160:163], v[184:187], v[124:127]
	v_mfma_f32_16x16x32_bf16 v[108:111], v[148:151], v[198:201], v[108:111]
	v_mfma_f32_16x16x32_bf16 v[104:107], v[160:163], v[198:201], v[104:107]
	v_mfma_f32_16x16x32_bf16 v[92:95], v[148:151], v[210:213], v[92:95]
	v_mfma_f32_16x16x32_bf16 v[88:91], v[160:163], v[210:213], v[88:91]
	v_mfma_f32_16x16x32_bf16 v[76:79], v[148:151], v[238:241], v[76:79]
	v_mfma_f32_16x16x32_bf16 v[72:75], v[160:163], v[238:241], v[72:75]
	v_mfma_f32_16x16x32_bf16 v[128:131], v[156:159], v[188:191], v[128:131]
	v_mfma_f32_16x16x32_bf16 v[124:127], v[164:167], v[188:191], v[124:127]
	v_mfma_f32_16x16x32_bf16 v[108:111], v[156:159], v[206:209], v[108:111]
	v_mfma_f32_16x16x32_bf16 v[104:107], v[164:167], v[206:209], v[104:107]
	v_mfma_f32_16x16x32_bf16 v[92:95], v[156:159], v[234:237], v[92:95]
	v_mfma_f32_16x16x32_bf16 v[88:91], v[164:167], v[234:237], v[88:91]
	v_mfma_f32_16x16x32_bf16 v[76:79], v[156:159], v[242:245], v[76:79]
	v_mfma_f32_16x16x32_bf16 v[72:75], v[164:167], v[242:245], v[72:75]
	v_mfma_f32_16x16x32_bf16 v[118:121], v[168:171], v[184:187], v[120:123]
	v_mfma_f32_16x16x32_bf16 v[114:117], v[176:179], v[184:187], v[114:117]
	v_mfma_f32_16x16x32_bf16 v[100:103], v[168:171], v[198:201], v[100:103]
	v_mfma_f32_16x16x32_bf16 v[96:99], v[176:179], v[198:201], v[96:99]
	v_mfma_f32_16x16x32_bf16 v[84:87], v[168:171], v[210:213], v[84:87]
	v_mfma_f32_16x16x32_bf16 v[80:83], v[176:179], v[210:213], v[80:83]
	v_mfma_f32_16x16x32_bf16 v[68:71], v[168:171], v[238:241], v[68:71]
	v_mfma_f32_16x16x32_bf16 v[64:67], v[176:179], v[238:241], v[64:67]
	v_mfma_f32_16x16x32_bf16 v[120:123], v[172:175], v[188:191], v[118:121]
	v_mfma_f32_16x16x32_bf16 v[116:119], v[180:183], v[188:191], v[114:117]
	v_mfma_f32_16x16x32_bf16 v[100:103], v[172:175], v[206:209], v[100:103]
	v_mfma_f32_16x16x32_bf16 v[96:99], v[180:183], v[206:209], v[96:99]
	v_mfma_f32_16x16x32_bf16 v[84:87], v[172:175], v[234:237], v[84:87]
	v_mfma_f32_16x16x32_bf16 v[80:83], v[180:183], v[234:237], v[80:83]
	v_mfma_f32_16x16x32_bf16 v[68:71], v[172:175], v[242:245], v[68:71]
	v_mfma_f32_16x16x32_bf16 v[64:67], v[180:183], v[242:245], v[64:67]
	s_barrier
	s_add_i32 s5, s5, s58
	v_lshl_add_u64 v[114:115], v[152:153], 0, s[48:49]
	s_mov_b32 m0, s5
	ds_read_b128 v[184:187], v155 offset:49152
	ds_read_b128 v[188:191], v155 offset:50176
	ds_read_b128 v[198:201], v155 offset:51200
	ds_read_b128 v[206:209], v155 offset:52224
	ds_read_b128 v[210:213], v155 offset:53248
	ds_read_b128 v[234:237], v155 offset:54272
	ds_read_b128 v[238:241], v155 offset:55296
	ds_read_b128 v[242:245], v155 offset:56320
	global_load_lds_dwordx4 v[114:115], off
	s_add_i32 m0, s5, 0x2000
	s_add_u32 s6, s16, 0x20080
	v_lshl_add_u64 v[114:115], v[192:193], 0, s[48:49]
	s_addc_u32 s7, s17, 0
	s_add_i32 s5, s9, s58
	global_load_lds_dwordx4 v[114:115], off
	v_lshl_add_u64 v[114:115], s[6:7], 0, v[134:135]
	s_mov_b32 m0, s5
	s_nop 0
	global_load_lds_dwordx4 v[114:115], off
	v_lshl_add_u64 v[114:115], s[6:7], 0, v[138:139]
	s_add_i32 m0, s5, 0x2000
	s_nop 0
	global_load_lds_dwordx4 v[114:115], off
	v_lshl_add_u64 v[114:115], v[246:247], 0, s[48:49]
	s_mov_b32 m0, s86
	s_nop 0
	global_load_lds_dwordx4 v[114:115], off
	v_lshl_add_u64 v[114:115], v[248:249], 0, s[48:49]
	s_mov_b32 m0, s87
	s_nop 0
	global_load_lds_dwordx4 v[114:115], off
	s_waitcnt vmcnt(8)
	s_waitcnt lgkmcnt(0)
	s_barrier
	s_waitcnt lgkmcnt(0)
	v_mfma_f32_16x16x32_bf16 v[60:63], v[148:151], v[184:187], v[60:63]
	v_mfma_f32_16x16x32_bf16 v[56:59], v[160:163], v[184:187], v[56:59]
	v_mfma_f32_16x16x32_bf16 v[44:47], v[148:151], v[198:201], v[44:47]
	v_mfma_f32_16x16x32_bf16 v[40:43], v[160:163], v[198:201], v[40:43]
	v_mfma_f32_16x16x32_bf16 v[28:31], v[148:151], v[210:213], v[28:31]
	v_mfma_f32_16x16x32_bf16 v[24:27], v[160:163], v[210:213], v[24:27]
	v_mfma_f32_16x16x32_bf16 v[12:15], v[148:151], v[238:241], v[12:15]
	v_mfma_f32_16x16x32_bf16 v[8:11], v[160:163], v[238:241], v[8:11]
	v_mfma_f32_16x16x32_bf16 v[60:63], v[156:159], v[188:191], v[60:63]
	v_mfma_f32_16x16x32_bf16 v[56:59], v[164:167], v[188:191], v[56:59]
	v_mfma_f32_16x16x32_bf16 v[44:47], v[156:159], v[206:209], v[44:47]
	v_mfma_f32_16x16x32_bf16 v[40:43], v[164:167], v[206:209], v[40:43]
	v_mfma_f32_16x16x32_bf16 v[28:31], v[156:159], v[234:237], v[28:31]
	v_mfma_f32_16x16x32_bf16 v[24:27], v[164:167], v[234:237], v[24:27]
	v_mfma_f32_16x16x32_bf16 v[12:15], v[156:159], v[242:245], v[12:15]
	v_mfma_f32_16x16x32_bf16 v[8:11], v[164:167], v[242:245], v[8:11]
	v_mfma_f32_16x16x32_bf16 v[52:55], v[168:171], v[184:187], v[52:55]
	v_mfma_f32_16x16x32_bf16 v[48:51], v[176:179], v[184:187], v[48:51]
	v_mfma_f32_16x16x32_bf16 v[36:39], v[168:171], v[198:201], v[36:39]
	v_mfma_f32_16x16x32_bf16 v[32:35], v[176:179], v[198:201], v[32:35]
	v_mfma_f32_16x16x32_bf16 v[20:23], v[168:171], v[210:213], v[20:23]
	v_mfma_f32_16x16x32_bf16 v[16:19], v[176:179], v[210:213], v[16:19]
	v_mfma_f32_16x16x32_bf16 v[4:7], v[168:171], v[238:241], v[4:7]
	v_mfma_f32_16x16x32_bf16 v[0:3], v[176:179], v[238:241], v[0:3]
	v_mfma_f32_16x16x32_bf16 v[52:55], v[172:175], v[188:191], v[52:55]
	v_mfma_f32_16x16x32_bf16 v[48:51], v[180:183], v[188:191], v[48:51]
	v_mfma_f32_16x16x32_bf16 v[36:39], v[172:175], v[206:209], v[36:39]
	v_mfma_f32_16x16x32_bf16 v[32:35], v[180:183], v[206:209], v[32:35]
	v_mfma_f32_16x16x32_bf16 v[20:23], v[172:175], v[234:237], v[20:23]
	v_mfma_f32_16x16x32_bf16 v[16:19], v[180:183], v[234:237], v[16:19]
	v_mfma_f32_16x16x32_bf16 v[4:7], v[172:175], v[242:245], v[4:7]
	v_mfma_f32_16x16x32_bf16 v[0:3], v[180:183], v[242:245], v[0:3]
	s_barrier
	s_cmp_lt_i32 s40, 14
	s_cbranch_scc1 .LBB1_623
	s_cmp_eq_u32 s40, 14
	s_cselect_b64 s[16:17], -1, 0
	s_cbranch_execz .LBB1_624
	s_branch .LBB1_625

.LBB1_721:
	s_add_u32 s82, s40, 0xfff80080
	s_addc_u32 s83, s41, -1
	s_add_i32 s92, 0, 0x10000
	s_cmp_eq_u32 s91, 28
	s_cselect_b32 s85, s39, s83
	s_cselect_b32 s84, s63, s82
	v_add_u32_e32 v112, s92, v170
	s_cselect_b32 s83, s72, s90
	s_cselect_b32 s82, s86, s87
	s_add_i32 s94, 0, 0x14000
	ds_read_b128 v[130:133], v112
	ds_read_b128 v[134:137], v112 offset:1024
	ds_read_b128 v[138:141], v112 offset:2048
	ds_read_b128 v[142:145], v112 offset:3072
	v_add_u32_e32 v112, s94, v170
	ds_read_b128 v[158:161], v112
	ds_read_b128 v[162:165], v112 offset:1024
	ds_read_b128 v[166:169], v112 offset:2048
	ds_read_b128 v[172:175], v112 offset:3072
	v_lshl_add_u64 v[192:193], s[40:41], 0, v[154:155]
	s_add_i32 m0, s9, 0xc000
	ds_read_b128 v[176:179], v171
	ds_read_b128 v[180:183], v171 offset:1024
	ds_read_b128 v[184:187], v171 offset:2048
	ds_read_b128 v[188:191], v171 offset:3072
	ds_read_b128 v[198:201], v171 offset:4096
	ds_read_b128 v[206:209], v171 offset:5120
	ds_read_b128 v[210:213], v171 offset:6144
	ds_read_b128 v[234:237], v171 offset:7168
	global_load_lds_dwordx4 v[192:193], off
	v_lshl_add_u64 v[192:193], s[40:41], 0, v[156:157]
	s_add_i32 m0, s9, 0xe000
	s_nop 0
	global_load_lds_dwordx4 v[192:193], off
	s_waitcnt vmcnt(8)
	s_waitcnt lgkmcnt(0)
	s_barrier
	s_waitcnt lgkmcnt(0)
	v_mfma_f32_16x16x32_bf16 v[126:129], v[130:133], v[176:179], v[126:129]
	v_mfma_f32_16x16x32_bf16 v[122:125], v[138:141], v[176:179], v[122:125]
	v_mfma_f32_16x16x32_bf16 v[108:111], v[130:133], v[184:187], v[108:111]
	v_mfma_f32_16x16x32_bf16 v[104:107], v[138:141], v[184:187], v[104:107]
	v_mfma_f32_16x16x32_bf16 v[92:95], v[130:133], v[198:201], v[92:95]
	v_mfma_f32_16x16x32_bf16 v[88:91], v[138:141], v[198:201], v[88:91]
	v_mfma_f32_16x16x32_bf16 v[76:79], v[130:133], v[210:213], v[76:79]
	v_mfma_f32_16x16x32_bf16 v[72:75], v[138:141], v[210:213], v[72:75]
	v_mfma_f32_16x16x32_bf16 v[126:129], v[134:137], v[180:183], v[126:129]
	v_mfma_f32_16x16x32_bf16 v[122:125], v[142:145], v[180:183], v[122:125]
	v_mfma_f32_16x16x32_bf16 v[108:111], v[134:137], v[188:191], v[108:111]
	v_mfma_f32_16x16x32_bf16 v[104:107], v[142:145], v[188:191], v[104:107]
	v_mfma_f32_16x16x32_bf16 v[92:95], v[134:137], v[206:209], v[92:95]
	v_mfma_f32_16x16x32_bf16 v[88:91], v[142:145], v[206:209], v[88:91]
	v_mfma_f32_16x16x32_bf16 v[76:79], v[134:137], v[234:237], v[76:79]
	v_mfma_f32_16x16x32_bf16 v[72:75], v[142:145], v[234:237], v[72:75]
	v_mfma_f32_16x16x32_bf16 v[118:121], v[158:161], v[176:179], v[118:121]
	v_mfma_f32_16x16x32_bf16 v[114:117], v[166:169], v[176:179], v[114:117]
	v_mfma_f32_16x16x32_bf16 v[100:103], v[158:161], v[184:187], v[100:103]
	v_mfma_f32_16x16x32_bf16 v[96:99], v[166:169], v[184:187], v[96:99]
	v_mfma_f32_16x16x32_bf16 v[84:87], v[158:161], v[198:201], v[84:87]
	v_mfma_f32_16x16x32_bf16 v[80:83], v[166:169], v[198:201], v[80:83]
	v_mfma_f32_16x16x32_bf16 v[68:71], v[158:161], v[210:213], v[68:71]
	v_mfma_f32_16x16x32_bf16 v[64:67], v[166:169], v[210:213], v[64:67]
	v_mfma_f32_16x16x32_bf16 v[118:121], v[162:165], v[180:183], v[118:121]
	v_mfma_f32_16x16x32_bf16 v[114:117], v[172:175], v[180:183], v[114:117]
	v_mfma_f32_16x16x32_bf16 v[100:103], v[162:165], v[188:191], v[100:103]
	v_mfma_f32_16x16x32_bf16 v[96:99], v[172:175], v[188:191], v[96:99]
	v_mfma_f32_16x16x32_bf16 v[84:87], v[162:165], v[206:209], v[84:87]
	v_mfma_f32_16x16x32_bf16 v[80:83], v[172:175], v[206:209], v[80:83]
	v_mfma_f32_16x16x32_bf16 v[68:71], v[162:165], v[234:237], v[68:71]
	v_mfma_f32_16x16x32_bf16 v[64:67], v[172:175], v[234:237], v[64:67]
	s_barrier
	s_add_i32 s92, s92, s7
	v_lshl_add_u64 v[192:193], s[82:83], 0, v[148:149]
	s_mov_b32 m0, s92
	ds_read_b128 v[176:179], v171 offset:16384
	ds_read_b128 v[180:183], v171 offset:17408
	ds_read_b128 v[184:187], v171 offset:18432
	ds_read_b128 v[188:191], v171 offset:19456
	ds_read_b128 v[198:201], v171 offset:20480
	ds_read_b128 v[206:209], v171 offset:21504
	ds_read_b128 v[210:213], v171 offset:22528
	ds_read_b128 v[234:237], v171 offset:23552
	global_load_lds_dwordx4 v[192:193], off
	s_add_i32 m0, s92, 0x2000
	s_add_u32 s92, s82, 0x20000
	v_lshl_add_u64 v[238:239], s[82:83], 0, v[152:153]
	s_addc_u32 s93, s83, 0
	s_add_i32 s94, s94, s7
	global_load_lds_dwordx4 v[238:239], off
	v_lshl_add_u64 v[240:241], s[92:93], 0, v[148:149]
	s_mov_b32 m0, s94
	v_lshl_add_u64 v[242:243], s[84:85], 0, v[150:151]
	global_load_lds_dwordx4 v[240:241], off
	v_lshl_add_u64 v[240:241], s[92:93], 0, v[152:153]
	s_add_i32 m0, s94, 0x2000
	s_nop 0
	global_load_lds_dwordx4 v[240:241], off
	s_waitcnt vmcnt(6)
	s_waitcnt lgkmcnt(0)
	s_barrier
	s_waitcnt lgkmcnt(0)
	v_mfma_f32_16x16x32_bf16 v[60:63], v[130:133], v[176:179], v[60:63]
	v_mfma_f32_16x16x32_bf16 v[56:59], v[138:141], v[176:179], v[56:59]
	v_mfma_f32_16x16x32_bf16 v[44:47], v[130:133], v[184:187], v[44:47]
	v_mfma_f32_16x16x32_bf16 v[40:43], v[138:141], v[184:187], v[40:43]
	v_mfma_f32_16x16x32_bf16 v[28:31], v[130:133], v[198:201], v[28:31]
	v_mfma_f32_16x16x32_bf16 v[24:27], v[138:141], v[198:201], v[24:27]
	v_mfma_f32_16x16x32_bf16 v[12:15], v[130:133], v[210:213], v[12:15]
	v_mfma_f32_16x16x32_bf16 v[8:11], v[138:141], v[210:213], v[8:11]
	v_mfma_f32_16x16x32_bf16 v[60:63], v[134:137], v[180:183], v[60:63]
	v_mfma_f32_16x16x32_bf16 v[56:59], v[142:145], v[180:183], v[56:59]
	v_mfma_f32_16x16x32_bf16 v[44:47], v[134:137], v[188:191], v[44:47]
	v_mfma_f32_16x16x32_bf16 v[40:43], v[142:145], v[188:191], v[40:43]
	v_mfma_f32_16x16x32_bf16 v[28:31], v[134:137], v[206:209], v[28:31]
	v_mfma_f32_16x16x32_bf16 v[24:27], v[142:145], v[206:209], v[24:27]
	v_mfma_f32_16x16x32_bf16 v[12:15], v[134:137], v[234:237], v[12:15]
	v_mfma_f32_16x16x32_bf16 v[8:11], v[142:145], v[234:237], v[8:11]
	v_mfma_f32_16x16x32_bf16 v[52:55], v[158:161], v[176:179], v[52:55]
	v_mfma_f32_16x16x32_bf16 v[48:51], v[166:169], v[176:179], v[48:51]
	v_mfma_f32_16x16x32_bf16 v[36:39], v[158:161], v[184:187], v[36:39]
	v_mfma_f32_16x16x32_bf16 v[32:35], v[166:169], v[184:187], v[32:35]
	v_mfma_f32_16x16x32_bf16 v[20:23], v[158:161], v[198:201], v[20:23]
	v_mfma_f32_16x16x32_bf16 v[16:19], v[166:169], v[198:201], v[16:19]
	v_mfma_f32_16x16x32_bf16 v[4:7], v[158:161], v[210:213], v[4:7]
	v_mfma_f32_16x16x32_bf16 v[0:3], v[166:169], v[210:213], v[0:3]
	v_mfma_f32_16x16x32_bf16 v[52:55], v[162:165], v[180:183], v[52:55]
	v_mfma_f32_16x16x32_bf16 v[48:51], v[172:175], v[180:183], v[48:51]
	v_mfma_f32_16x16x32_bf16 v[36:39], v[162:165], v[188:191], v[36:39]
	v_mfma_f32_16x16x32_bf16 v[32:35], v[172:175], v[188:191], v[32:35]
	v_mfma_f32_16x16x32_bf16 v[20:23], v[162:165], v[206:209], v[20:23]
	v_mfma_f32_16x16x32_bf16 v[16:19], v[172:175], v[206:209], v[16:19]
	v_mfma_f32_16x16x32_bf16 v[4:7], v[162:165], v[234:237], v[4:7]
	v_mfma_f32_16x16x32_bf16 v[0:3], v[172:175], v[234:237], v[0:3]
	s_barrier
	s_add_i32 s92, 0, 0x18000
	v_add_u32_e32 v112, s92, v170
	s_add_i32 s93, 0, 0x1c000
	ds_read_b128 v[130:133], v112
	ds_read_b128 v[134:137], v112 offset:1024
	ds_read_b128 v[138:141], v112 offset:2048
	ds_read_b128 v[142:145], v112 offset:3072
	v_add_u32_e32 v112, s93, v170
	ds_read_b128 v[158:161], v112
	ds_read_b128 v[162:165], v112 offset:1024
	ds_read_b128 v[166:169], v112 offset:2048
	ds_read_b128 v[172:175], v112 offset:3072
	v_lshl_add_u64 v[240:241], s[84:85], 0, v[146:147]
	s_mov_b32 m0, s9
	s_nop 0
	global_load_lds_dwordx4 v[240:241], off
	s_mov_b32 m0, s10
	s_nop 0
	global_load_lds_dwordx4 v[242:243], off
	s_add_u32 s84, s84, 0x80000
	s_addc_u32 s85, s85, 0
	s_mov_b32 m0, s11
	v_lshl_add_u64 v[244:245], s[84:85], 0, v[146:147]
	ds_read_b128 v[176:179], v171 offset:32768
	ds_read_b128 v[180:183], v171 offset:33792
	ds_read_b128 v[184:187], v171 offset:34816
	ds_read_b128 v[188:191], v171 offset:35840
	ds_read_b128 v[198:201], v171 offset:36864
	ds_read_b128 v[206:209], v171 offset:37888
	ds_read_b128 v[210:213], v171 offset:38912
	ds_read_b128 v[234:237], v171 offset:39936
	global_load_lds_dwordx4 v[244:245], off
	v_lshl_add_u64 v[244:245], s[84:85], 0, v[150:151]
	s_mov_b32 m0, s24
	s_nop 0
	global_load_lds_dwordx4 v[244:245], off
	s_waitcnt vmcnt(8)
	s_waitcnt lgkmcnt(0)
	s_barrier
	s_waitcnt lgkmcnt(0)
	v_mfma_f32_16x16x32_bf16 v[126:129], v[130:133], v[176:179], v[126:129]
	v_mfma_f32_16x16x32_bf16 v[122:125], v[138:141], v[176:179], v[122:125]
	v_mfma_f32_16x16x32_bf16 v[108:111], v[130:133], v[184:187], v[108:111]
	v_mfma_f32_16x16x32_bf16 v[104:107], v[138:141], v[184:187], v[104:107]
	v_mfma_f32_16x16x32_bf16 v[92:95], v[130:133], v[198:201], v[92:95]
	v_mfma_f32_16x16x32_bf16 v[88:91], v[138:141], v[198:201], v[88:91]
	v_mfma_f32_16x16x32_bf16 v[76:79], v[130:133], v[210:213], v[76:79]
	v_mfma_f32_16x16x32_bf16 v[72:75], v[138:141], v[210:213], v[72:75]
	v_mfma_f32_16x16x32_bf16 v[126:129], v[134:137], v[180:183], v[126:129]
	v_mfma_f32_16x16x32_bf16 v[122:125], v[142:145], v[180:183], v[122:125]
	v_mfma_f32_16x16x32_bf16 v[108:111], v[134:137], v[188:191], v[108:111]
	v_mfma_f32_16x16x32_bf16 v[104:107], v[142:145], v[188:191], v[104:107]
	v_mfma_f32_16x16x32_bf16 v[92:95], v[134:137], v[206:209], v[92:95]
	v_mfma_f32_16x16x32_bf16 v[88:91], v[142:145], v[206:209], v[88:91]
	v_mfma_f32_16x16x32_bf16 v[76:79], v[134:137], v[234:237], v[76:79]
	v_mfma_f32_16x16x32_bf16 v[72:75], v[142:145], v[234:237], v[72:75]
	v_mfma_f32_16x16x32_bf16 v[118:121], v[158:161], v[176:179], v[118:121]
	v_mfma_f32_16x16x32_bf16 v[114:117], v[166:169], v[176:179], v[114:117]
	v_mfma_f32_16x16x32_bf16 v[100:103], v[158:161], v[184:187], v[100:103]
	v_mfma_f32_16x16x32_bf16 v[96:99], v[166:169], v[184:187], v[96:99]
	v_mfma_f32_16x16x32_bf16 v[84:87], v[158:161], v[198:201], v[84:87]
	v_mfma_f32_16x16x32_bf16 v[80:83], v[166:169], v[198:201], v[80:83]
	v_mfma_f32_16x16x32_bf16 v[68:71], v[158:161], v[210:213], v[68:71]
	v_mfma_f32_16x16x32_bf16 v[64:67], v[166:169], v[210:213], v[64:67]
	v_mfma_f32_16x16x32_bf16 v[118:121], v[162:165], v[180:183], v[118:121]
	v_mfma_f32_16x16x32_bf16 v[114:117], v[172:175], v[180:183], v[114:117]
	v_mfma_f32_16x16x32_bf16 v[100:103], v[162:165], v[188:191], v[100:103]
	v_mfma_f32_16x16x32_bf16 v[96:99], v[172:175], v[188:191], v[96:99]
	v_mfma_f32_16x16x32_bf16 v[84:87], v[162:165], v[206:209], v[84:87]
	v_mfma_f32_16x16x32_bf16 v[80:83], v[172:175], v[206:209], v[80:83]
	v_mfma_f32_16x16x32_bf16 v[68:71], v[162:165], v[234:237], v[68:71]
	v_mfma_f32_16x16x32_bf16 v[64:67], v[172:175], v[234:237], v[64:67]
	s_barrier
	s_add_i32 s84, s92, s7
	v_lshl_add_u64 v[192:193], v[192:193], 0, s[48:49]
	s_mov_b32 m0, s84
	ds_read_b128 v[176:179], v171 offset:49152
	ds_read_b128 v[180:183], v171 offset:50176
	ds_read_b128 v[184:187], v171 offset:51200
	ds_read_b128 v[188:191], v171 offset:52224
	ds_read_b128 v[198:201], v171 offset:53248
	ds_read_b128 v[206:209], v171 offset:54272
	ds_read_b128 v[210:213], v171 offset:55296
	ds_read_b128 v[234:237], v171 offset:56320
	global_load_lds_dwordx4 v[192:193], off
	s_add_i32 m0, s84, 0x2000
	s_add_u32 s82, s82, 0x20080
	v_lshl_add_u64 v[192:193], v[238:239], 0, s[48:49]
	s_addc_u32 s83, s83, 0
	s_add_i32 s84, s93, s7
	global_load_lds_dwordx4 v[192:193], off
	v_lshl_add_u64 v[192:193], s[82:83], 0, v[148:149]
	s_mov_b32 m0, s84
	s_nop 0
	global_load_lds_dwordx4 v[192:193], off
	v_lshl_add_u64 v[192:193], s[82:83], 0, v[152:153]
	s_add_i32 m0, s84, 0x2000
	s_nop 0
	global_load_lds_dwordx4 v[192:193], off
	v_lshl_add_u64 v[192:193], v[240:241], 0, s[48:49]
	s_mov_b32 m0, s55
	s_nop 0
	global_load_lds_dwordx4 v[192:193], off
	v_lshl_add_u64 v[192:193], v[242:243], 0, s[48:49]
	s_mov_b32 m0, s56
	s_nop 0
	global_load_lds_dwordx4 v[192:193], off
	s_waitcnt vmcnt(8)
	s_waitcnt lgkmcnt(0)
	s_barrier
	s_waitcnt lgkmcnt(0)
	v_mfma_f32_16x16x32_bf16 v[60:63], v[130:133], v[176:179], v[60:63]
	v_mfma_f32_16x16x32_bf16 v[56:59], v[138:141], v[176:179], v[56:59]
	v_mfma_f32_16x16x32_bf16 v[44:47], v[130:133], v[184:187], v[44:47]
	v_mfma_f32_16x16x32_bf16 v[40:43], v[138:141], v[184:187], v[40:43]
	v_mfma_f32_16x16x32_bf16 v[28:31], v[130:133], v[198:201], v[28:31]
	v_mfma_f32_16x16x32_bf16 v[24:27], v[138:141], v[198:201], v[24:27]
	v_mfma_f32_16x16x32_bf16 v[12:15], v[130:133], v[210:213], v[12:15]
	v_mfma_f32_16x16x32_bf16 v[8:11], v[138:141], v[210:213], v[8:11]
	v_mfma_f32_16x16x32_bf16 v[60:63], v[134:137], v[180:183], v[60:63]
	v_mfma_f32_16x16x32_bf16 v[56:59], v[142:145], v[180:183], v[56:59]
	v_mfma_f32_16x16x32_bf16 v[44:47], v[134:137], v[188:191], v[44:47]
	v_mfma_f32_16x16x32_bf16 v[40:43], v[142:145], v[188:191], v[40:43]
	v_mfma_f32_16x16x32_bf16 v[28:31], v[134:137], v[206:209], v[28:31]
	v_mfma_f32_16x16x32_bf16 v[24:27], v[142:145], v[206:209], v[24:27]
	v_mfma_f32_16x16x32_bf16 v[12:15], v[134:137], v[234:237], v[12:15]
	v_mfma_f32_16x16x32_bf16 v[8:11], v[142:145], v[234:237], v[8:11]
	v_mfma_f32_16x16x32_bf16 v[52:55], v[158:161], v[176:179], v[52:55]
	v_mfma_f32_16x16x32_bf16 v[48:51], v[166:169], v[176:179], v[48:51]
	v_mfma_f32_16x16x32_bf16 v[36:39], v[158:161], v[184:187], v[36:39]
	v_mfma_f32_16x16x32_bf16 v[32:35], v[166:169], v[184:187], v[32:35]
	v_mfma_f32_16x16x32_bf16 v[20:23], v[158:161], v[198:201], v[20:23]
	v_mfma_f32_16x16x32_bf16 v[16:19], v[166:169], v[198:201], v[16:19]
	v_mfma_f32_16x16x32_bf16 v[4:7], v[158:161], v[210:213], v[4:7]
	v_mfma_f32_16x16x32_bf16 v[0:3], v[166:169], v[210:213], v[0:3]
	v_mfma_f32_16x16x32_bf16 v[52:55], v[162:165], v[180:183], v[52:55]
	v_mfma_f32_16x16x32_bf16 v[48:51], v[172:175], v[180:183], v[48:51]
	v_mfma_f32_16x16x32_bf16 v[36:39], v[162:165], v[188:191], v[36:39]
	v_mfma_f32_16x16x32_bf16 v[32:35], v[172:175], v[188:191], v[32:35]
	v_mfma_f32_16x16x32_bf16 v[20:23], v[162:165], v[206:209], v[20:23]
	v_mfma_f32_16x16x32_bf16 v[16:19], v[172:175], v[206:209], v[16:19]
	v_mfma_f32_16x16x32_bf16 v[4:7], v[162:165], v[234:237], v[4:7]
	v_mfma_f32_16x16x32_bf16 v[0:3], v[172:175], v[234:237], v[0:3]
	s_barrier
	s_add_i32 s91, s91, 2
	s_add_u32 s40, s40, 0x100
	s_addc_u32 s41, s41, 0
	s_add_u32 s87, s87, 0x100
	s_addc_u32 s90, s90, 0
	s_cmp_gt_u32 s91, 29
	s_cbranch_scc0 .LBB1_721
	s_and_b64 vcc, exec, s[26:27]
	s_cbranch_vccz .LBB1_724
	s_barrier

.LBB1_939:
	s_add_u32 s38, s26, 0xfff80080
	s_addc_u32 s39, s27, -1
	s_add_i32 s94, 0, 0x10000
	s_cmp_eq_u32 vcc_lo, 28
	s_cselect_b32 s41, s19, s39
	s_cselect_b32 s40, s31, s38
	v_add_u32_e32 v112, s94, v166
	s_cselect_b32 s39, s42, s45
	s_cselect_b32 s38, s43, s44
	s_add_i32 vcc_hi, 0, 0x14000
	ds_read_b128 v[130:133], v112
	ds_read_b128 v[134:137], v112 offset:1024
	ds_read_b128 v[138:141], v112 offset:2048
	ds_read_b128 v[142:145], v112 offset:3072
	v_add_u32_e32 v112, vcc_hi, v166
	ds_read_b128 v[146:149], v112
	ds_read_b128 v[150:153], v112 offset:1024
	ds_read_b128 v[168:171], v112 offset:2048
	ds_read_b128 v[172:175], v112 offset:3072
	v_lshl_add_u64 v[192:193], s[26:27], 0, v[162:163]
	s_add_i32 m0, s7, 0xc000
	ds_read_b128 v[176:179], v167
	ds_read_b128 v[180:183], v167 offset:1024
	ds_read_b128 v[184:187], v167 offset:2048
	ds_read_b128 v[188:191], v167 offset:3072
	ds_read_b128 v[198:201], v167 offset:4096
	ds_read_b128 v[206:209], v167 offset:5120
	ds_read_b128 v[210:213], v167 offset:6144
	ds_read_b128 v[234:237], v167 offset:7168
	global_load_lds_dwordx4 v[192:193], off
	v_lshl_add_u64 v[192:193], s[26:27], 0, v[164:165]
	s_add_i32 m0, s7, 0xe000
	s_nop 0
	global_load_lds_dwordx4 v[192:193], off
	s_waitcnt vmcnt(8)
	s_waitcnt lgkmcnt(0)
	s_barrier
	s_waitcnt lgkmcnt(0)
	v_mfma_f32_16x16x32_bf16 v[108:111], v[130:133], v[176:179], v[108:111]
	v_mfma_f32_16x16x32_bf16 v[84:87], v[138:141], v[176:179], v[84:87]
	v_mfma_f32_16x16x32_bf16 v[126:129], v[130:133], v[184:187], v[126:129]
	v_mfma_f32_16x16x32_bf16 v[92:95], v[138:141], v[184:187], v[92:95]
	v_mfma_f32_16x16x32_bf16 v[122:125], v[130:133], v[198:201], v[122:125]
	v_mfma_f32_16x16x32_bf16 v[88:91], v[138:141], v[198:201], v[88:91]
	v_mfma_f32_16x16x32_bf16 v[104:107], v[130:133], v[210:213], v[104:107]
	v_mfma_f32_16x16x32_bf16 v[76:79], v[138:141], v[210:213], v[76:79]
	v_mfma_f32_16x16x32_bf16 v[108:111], v[134:137], v[180:183], v[108:111]
	v_mfma_f32_16x16x32_bf16 v[84:87], v[142:145], v[180:183], v[84:87]
	v_mfma_f32_16x16x32_bf16 v[126:129], v[134:137], v[188:191], v[126:129]
	v_mfma_f32_16x16x32_bf16 v[92:95], v[142:145], v[188:191], v[92:95]
	v_mfma_f32_16x16x32_bf16 v[122:125], v[134:137], v[206:209], v[122:125]
	v_mfma_f32_16x16x32_bf16 v[88:91], v[142:145], v[206:209], v[88:91]
	v_mfma_f32_16x16x32_bf16 v[104:107], v[134:137], v[234:237], v[104:107]
	v_mfma_f32_16x16x32_bf16 v[76:79], v[142:145], v[234:237], v[76:79]
	v_mfma_f32_16x16x32_bf16 v[100:103], v[146:149], v[176:179], v[100:103]
	v_mfma_f32_16x16x32_bf16 v[68:71], v[168:171], v[176:179], v[68:71]
	v_mfma_f32_16x16x32_bf16 v[118:121], v[146:149], v[184:187], v[118:121]
	v_mfma_f32_16x16x32_bf16 v[80:83], v[168:171], v[184:187], v[80:83]
	v_mfma_f32_16x16x32_bf16 v[114:117], v[146:149], v[198:201], v[114:117]
	v_mfma_f32_16x16x32_bf16 v[72:75], v[168:171], v[198:201], v[72:75]
	v_mfma_f32_16x16x32_bf16 v[96:99], v[146:149], v[210:213], v[96:99]
	v_mfma_f32_16x16x32_bf16 v[64:67], v[168:171], v[210:213], v[64:67]
	v_mfma_f32_16x16x32_bf16 v[100:103], v[150:153], v[180:183], v[100:103]
	v_mfma_f32_16x16x32_bf16 v[68:71], v[172:175], v[180:183], v[68:71]
	v_mfma_f32_16x16x32_bf16 v[118:121], v[150:153], v[188:191], v[118:121]
	v_mfma_f32_16x16x32_bf16 v[80:83], v[172:175], v[188:191], v[80:83]
	v_mfma_f32_16x16x32_bf16 v[114:117], v[150:153], v[206:209], v[114:117]
	v_mfma_f32_16x16x32_bf16 v[72:75], v[172:175], v[206:209], v[72:75]
	v_mfma_f32_16x16x32_bf16 v[96:99], v[150:153], v[234:237], v[96:99]
	v_mfma_f32_16x16x32_bf16 v[64:67], v[172:175], v[234:237], v[64:67]
	s_barrier
	s_add_i32 s94, s94, s6
	v_lshl_add_u64 v[192:193], s[38:39], 0, v[156:157]
	s_mov_b32 m0, s94
	ds_read_b128 v[176:179], v167 offset:16384
	ds_read_b128 v[180:183], v167 offset:17408
	ds_read_b128 v[184:187], v167 offset:18432
	ds_read_b128 v[188:191], v167 offset:19456
	ds_read_b128 v[198:201], v167 offset:20480
	ds_read_b128 v[206:209], v167 offset:21504
	ds_read_b128 v[210:213], v167 offset:22528
	ds_read_b128 v[234:237], v167 offset:23552
	global_load_lds_dwordx4 v[192:193], off
	s_add_i32 m0, s94, 0x2000
	s_add_u32 s94, s38, 0x20000
	v_lshl_add_u64 v[238:239], s[38:39], 0, v[160:161]
	s_addc_u32 s95, s39, 0
	s_add_i32 vcc_hi, vcc_hi, s6
	global_load_lds_dwordx4 v[238:239], off
	v_lshl_add_u64 v[240:241], s[94:95], 0, v[156:157]
	s_mov_b32 m0, vcc_hi
	v_lshl_add_u64 v[242:243], s[40:41], 0, v[158:159]
	global_load_lds_dwordx4 v[240:241], off
	v_lshl_add_u64 v[240:241], s[94:95], 0, v[160:161]
	s_add_i32 m0, vcc_hi, 0x2000
	s_nop 0
	global_load_lds_dwordx4 v[240:241], off
	s_waitcnt vmcnt(6)
	s_waitcnt lgkmcnt(0)
	s_barrier
	s_waitcnt lgkmcnt(0)
	v_mfma_f32_16x16x32_bf16 v[52:55], v[130:133], v[176:179], v[52:55]
	v_mfma_f32_16x16x32_bf16 v[20:23], v[138:141], v[176:179], v[20:23]
	v_mfma_f32_16x16x32_bf16 v[60:63], v[130:133], v[184:187], v[60:63]
	v_mfma_f32_16x16x32_bf16 v[28:31], v[138:141], v[184:187], v[28:31]
	v_mfma_f32_16x16x32_bf16 v[56:59], v[130:133], v[198:201], v[56:59]
	v_mfma_f32_16x16x32_bf16 v[24:27], v[138:141], v[198:201], v[24:27]
	v_mfma_f32_16x16x32_bf16 v[48:51], v[130:133], v[210:213], v[48:51]
	v_mfma_f32_16x16x32_bf16 v[16:19], v[138:141], v[210:213], v[16:19]
	v_mfma_f32_16x16x32_bf16 v[52:55], v[134:137], v[180:183], v[52:55]
	v_mfma_f32_16x16x32_bf16 v[20:23], v[142:145], v[180:183], v[20:23]
	v_mfma_f32_16x16x32_bf16 v[60:63], v[134:137], v[188:191], v[60:63]
	v_mfma_f32_16x16x32_bf16 v[28:31], v[142:145], v[188:191], v[28:31]
	v_mfma_f32_16x16x32_bf16 v[56:59], v[134:137], v[206:209], v[56:59]
	v_mfma_f32_16x16x32_bf16 v[24:27], v[142:145], v[206:209], v[24:27]
	v_mfma_f32_16x16x32_bf16 v[48:51], v[134:137], v[234:237], v[48:51]
	v_mfma_f32_16x16x32_bf16 v[16:19], v[142:145], v[234:237], v[16:19]
	v_mfma_f32_16x16x32_bf16 v[36:39], v[146:149], v[176:179], v[36:39]
	v_mfma_f32_16x16x32_bf16 v[4:7], v[168:171], v[176:179], v[4:7]
	v_mfma_f32_16x16x32_bf16 v[44:47], v[146:149], v[184:187], v[44:47]
	v_mfma_f32_16x16x32_bf16 v[12:15], v[168:171], v[184:187], v[12:15]
	v_mfma_f32_16x16x32_bf16 v[40:43], v[146:149], v[198:201], v[40:43]
	v_mfma_f32_16x16x32_bf16 v[8:11], v[168:171], v[198:201], v[8:11]
	v_mfma_f32_16x16x32_bf16 v[32:35], v[146:149], v[210:213], v[32:35]
	v_mfma_f32_16x16x32_bf16 v[0:3], v[168:171], v[210:213], v[0:3]
	v_mfma_f32_16x16x32_bf16 v[36:39], v[150:153], v[180:183], v[36:39]
	v_mfma_f32_16x16x32_bf16 v[4:7], v[172:175], v[180:183], v[4:7]
	v_mfma_f32_16x16x32_bf16 v[44:47], v[150:153], v[188:191], v[44:47]
	v_mfma_f32_16x16x32_bf16 v[12:15], v[172:175], v[188:191], v[12:15]
	v_mfma_f32_16x16x32_bf16 v[40:43], v[150:153], v[206:209], v[40:43]
	v_mfma_f32_16x16x32_bf16 v[8:11], v[172:175], v[206:209], v[8:11]
	v_mfma_f32_16x16x32_bf16 v[32:35], v[150:153], v[234:237], v[32:35]
	v_mfma_f32_16x16x32_bf16 v[0:3], v[172:175], v[234:237], v[0:3]
	s_barrier
	s_add_i32 s94, 0, 0x18000
	v_add_u32_e32 v112, s94, v166
	s_add_i32 s95, 0, 0x1c000
	ds_read_b128 v[130:133], v112
	ds_read_b128 v[134:137], v112 offset:1024
	ds_read_b128 v[138:141], v112 offset:2048
	ds_read_b128 v[142:145], v112 offset:3072
	v_add_u32_e32 v112, s95, v166
	ds_read_b128 v[146:149], v112
	ds_read_b128 v[150:153], v112 offset:1024
	ds_read_b128 v[168:171], v112 offset:2048
	ds_read_b128 v[172:175], v112 offset:3072
	v_lshl_add_u64 v[240:241], s[40:41], 0, v[154:155]
	s_mov_b32 m0, s7
	s_nop 0
	global_load_lds_dwordx4 v[240:241], off
	s_mov_b32 m0, s2
	s_nop 0
	global_load_lds_dwordx4 v[242:243], off
	s_add_u32 s40, s40, 0x80000
	s_addc_u32 s41, s41, 0
	s_mov_b32 m0, s3
	v_lshl_add_u64 v[244:245], s[40:41], 0, v[154:155]
	ds_read_b128 v[176:179], v167 offset:32768
	ds_read_b128 v[180:183], v167 offset:33792
	ds_read_b128 v[184:187], v167 offset:34816
	ds_read_b128 v[188:191], v167 offset:35840
	ds_read_b128 v[198:201], v167 offset:36864
	ds_read_b128 v[206:209], v167 offset:37888
	ds_read_b128 v[210:213], v167 offset:38912
	ds_read_b128 v[234:237], v167 offset:39936
	global_load_lds_dwordx4 v[244:245], off
	v_lshl_add_u64 v[244:245], s[40:41], 0, v[158:159]
	s_mov_b32 m0, s5
	s_nop 0
	global_load_lds_dwordx4 v[244:245], off
	s_waitcnt vmcnt(8)
	s_waitcnt lgkmcnt(0)
	s_barrier
	s_waitcnt lgkmcnt(0)
	v_mfma_f32_16x16x32_bf16 v[108:111], v[130:133], v[176:179], v[108:111]
	v_mfma_f32_16x16x32_bf16 v[84:87], v[138:141], v[176:179], v[84:87]
	v_mfma_f32_16x16x32_bf16 v[126:129], v[130:133], v[184:187], v[126:129]
	v_mfma_f32_16x16x32_bf16 v[92:95], v[138:141], v[184:187], v[92:95]
	v_mfma_f32_16x16x32_bf16 v[122:125], v[130:133], v[198:201], v[122:125]
	v_mfma_f32_16x16x32_bf16 v[88:91], v[138:141], v[198:201], v[88:91]
	v_mfma_f32_16x16x32_bf16 v[104:107], v[130:133], v[210:213], v[104:107]
	v_mfma_f32_16x16x32_bf16 v[76:79], v[138:141], v[210:213], v[76:79]
	v_mfma_f32_16x16x32_bf16 v[108:111], v[134:137], v[180:183], v[108:111]
	v_mfma_f32_16x16x32_bf16 v[84:87], v[142:145], v[180:183], v[84:87]
	v_mfma_f32_16x16x32_bf16 v[126:129], v[134:137], v[188:191], v[126:129]
	v_mfma_f32_16x16x32_bf16 v[92:95], v[142:145], v[188:191], v[92:95]
	v_mfma_f32_16x16x32_bf16 v[122:125], v[134:137], v[206:209], v[122:125]
	v_mfma_f32_16x16x32_bf16 v[88:91], v[142:145], v[206:209], v[88:91]
	v_mfma_f32_16x16x32_bf16 v[104:107], v[134:137], v[234:237], v[104:107]
	v_mfma_f32_16x16x32_bf16 v[76:79], v[142:145], v[234:237], v[76:79]
	v_mfma_f32_16x16x32_bf16 v[100:103], v[146:149], v[176:179], v[100:103]
	v_mfma_f32_16x16x32_bf16 v[68:71], v[168:171], v[176:179], v[68:71]
	v_mfma_f32_16x16x32_bf16 v[118:121], v[146:149], v[184:187], v[118:121]
	v_mfma_f32_16x16x32_bf16 v[80:83], v[168:171], v[184:187], v[80:83]
	v_mfma_f32_16x16x32_bf16 v[114:117], v[146:149], v[198:201], v[114:117]
	v_mfma_f32_16x16x32_bf16 v[72:75], v[168:171], v[198:201], v[72:75]
	v_mfma_f32_16x16x32_bf16 v[96:99], v[146:149], v[210:213], v[96:99]
	v_mfma_f32_16x16x32_bf16 v[64:67], v[168:171], v[210:213], v[64:67]
	v_mfma_f32_16x16x32_bf16 v[100:103], v[150:153], v[180:183], v[100:103]
	v_mfma_f32_16x16x32_bf16 v[68:71], v[172:175], v[180:183], v[68:71]
	v_mfma_f32_16x16x32_bf16 v[118:121], v[150:153], v[188:191], v[118:121]
	v_mfma_f32_16x16x32_bf16 v[80:83], v[172:175], v[188:191], v[80:83]
	v_mfma_f32_16x16x32_bf16 v[114:117], v[150:153], v[206:209], v[114:117]
	v_mfma_f32_16x16x32_bf16 v[72:75], v[172:175], v[206:209], v[72:75]
	v_mfma_f32_16x16x32_bf16 v[96:99], v[150:153], v[234:237], v[96:99]
	v_mfma_f32_16x16x32_bf16 v[64:67], v[172:175], v[234:237], v[64:67]
	s_barrier
	s_add_i32 s40, s94, s6
	v_lshl_add_u64 v[192:193], v[192:193], 0, s[48:49]
	s_mov_b32 m0, s40
	ds_read_b128 v[176:179], v167 offset:49152
	ds_read_b128 v[180:183], v167 offset:50176
	ds_read_b128 v[184:187], v167 offset:51200
	ds_read_b128 v[188:191], v167 offset:52224
	ds_read_b128 v[198:201], v167 offset:53248
	ds_read_b128 v[206:209], v167 offset:54272
	ds_read_b128 v[210:213], v167 offset:55296
	ds_read_b128 v[234:237], v167 offset:56320
	global_load_lds_dwordx4 v[192:193], off
	s_add_i32 m0, s40, 0x2000
	s_add_u32 s38, s38, 0x20080
	v_lshl_add_u64 v[192:193], v[238:239], 0, s[48:49]
	s_addc_u32 s39, s39, 0
	s_add_i32 s40, s95, s6
	global_load_lds_dwordx4 v[192:193], off
	v_lshl_add_u64 v[192:193], s[38:39], 0, v[156:157]
	s_mov_b32 m0, s40
	s_nop 0
	global_load_lds_dwordx4 v[192:193], off
	v_lshl_add_u64 v[192:193], s[38:39], 0, v[160:161]
	s_add_i32 m0, s40, 0x2000
	s_nop 0
	global_load_lds_dwordx4 v[192:193], off
	v_lshl_add_u64 v[192:193], v[240:241], 0, s[48:49]
	s_mov_b32 m0, s67
	s_nop 0
	global_load_lds_dwordx4 v[192:193], off
	v_lshl_add_u64 v[192:193], v[242:243], 0, s[48:49]
	s_mov_b32 m0, s9
	s_nop 0
	global_load_lds_dwordx4 v[192:193], off
	s_waitcnt vmcnt(8)
	s_waitcnt lgkmcnt(0)
	s_barrier
	s_waitcnt lgkmcnt(0)
	v_mfma_f32_16x16x32_bf16 v[52:55], v[130:133], v[176:179], v[52:55]
	v_mfma_f32_16x16x32_bf16 v[20:23], v[138:141], v[176:179], v[20:23]
	v_mfma_f32_16x16x32_bf16 v[60:63], v[130:133], v[184:187], v[60:63]
	v_mfma_f32_16x16x32_bf16 v[28:31], v[138:141], v[184:187], v[28:31]
	v_mfma_f32_16x16x32_bf16 v[56:59], v[130:133], v[198:201], v[56:59]
	v_mfma_f32_16x16x32_bf16 v[24:27], v[138:141], v[198:201], v[24:27]
	v_mfma_f32_16x16x32_bf16 v[48:51], v[130:133], v[210:213], v[48:51]
	v_mfma_f32_16x16x32_bf16 v[16:19], v[138:141], v[210:213], v[16:19]
	v_mfma_f32_16x16x32_bf16 v[52:55], v[134:137], v[180:183], v[52:55]
	v_mfma_f32_16x16x32_bf16 v[20:23], v[142:145], v[180:183], v[20:23]
	v_mfma_f32_16x16x32_bf16 v[60:63], v[134:137], v[188:191], v[60:63]
	v_mfma_f32_16x16x32_bf16 v[28:31], v[142:145], v[188:191], v[28:31]
	v_mfma_f32_16x16x32_bf16 v[56:59], v[134:137], v[206:209], v[56:59]
	v_mfma_f32_16x16x32_bf16 v[24:27], v[142:145], v[206:209], v[24:27]
	v_mfma_f32_16x16x32_bf16 v[48:51], v[134:137], v[234:237], v[48:51]
	v_mfma_f32_16x16x32_bf16 v[16:19], v[142:145], v[234:237], v[16:19]
	v_mfma_f32_16x16x32_bf16 v[36:39], v[146:149], v[176:179], v[36:39]
	v_mfma_f32_16x16x32_bf16 v[4:7], v[168:171], v[176:179], v[4:7]
	v_mfma_f32_16x16x32_bf16 v[44:47], v[146:149], v[184:187], v[44:47]
	v_mfma_f32_16x16x32_bf16 v[12:15], v[168:171], v[184:187], v[12:15]
	v_mfma_f32_16x16x32_bf16 v[40:43], v[146:149], v[198:201], v[40:43]
	v_mfma_f32_16x16x32_bf16 v[8:11], v[168:171], v[198:201], v[8:11]
	v_mfma_f32_16x16x32_bf16 v[32:35], v[146:149], v[210:213], v[32:35]
	v_mfma_f32_16x16x32_bf16 v[0:3], v[168:171], v[210:213], v[0:3]
	v_mfma_f32_16x16x32_bf16 v[36:39], v[150:153], v[180:183], v[36:39]
	v_mfma_f32_16x16x32_bf16 v[4:7], v[172:175], v[180:183], v[4:7]
	v_mfma_f32_16x16x32_bf16 v[44:47], v[150:153], v[188:191], v[44:47]
	v_mfma_f32_16x16x32_bf16 v[12:15], v[172:175], v[188:191], v[12:15]
	v_mfma_f32_16x16x32_bf16 v[40:43], v[150:153], v[206:209], v[40:43]
	v_mfma_f32_16x16x32_bf16 v[8:11], v[172:175], v[206:209], v[8:11]
	v_mfma_f32_16x16x32_bf16 v[32:35], v[150:153], v[234:237], v[32:35]
	v_mfma_f32_16x16x32_bf16 v[0:3], v[172:175], v[234:237], v[0:3]
	s_barrier
	s_add_i32 vcc_lo, vcc_lo, 2
	s_add_u32 s26, s26, 0x100
	s_addc_u32 s27, s27, 0
	s_add_u32 s44, s44, 0x100
	s_addc_u32 s45, s45, 0
	s_cmp_gt_u32 vcc_lo, 29
	s_cbranch_scc0 .LBB1_939
	s_and_b64 vcc, exec, s[80:81]
	s_cbranch_vccz .LBB1_942
	s_barrier

.LBB1_1254:
	s_add_u32 s60, s26, 0x100
	s_addc_u32 s61, s27, 0
	s_add_i32 s84, 0, 0x10000
	s_cmpk_eq_i32 s83, 0x54
	s_cselect_b32 s75, s77, s61
	s_cselect_b32 s74, s78, s60
	v_add_u32_e32 v144, s84, v146
	s_cselect_b32 s63, s79, s82
	s_cselect_b32 s62, s80, s81
	s_add_i32 s85, 0, 0x14000
	ds_read_b128 v[140:143], v144
	ds_read_b128 v[148:151], v144 offset:1024
	ds_read_b128 v[152:155], v144 offset:2048
	ds_read_b128 v[156:159], v144 offset:3072
	v_add_u32_e32 v144, s85, v146
	ds_read_b128 v[160:163], v144
	ds_read_b128 v[164:167], v144 offset:1024
	ds_read_b128 v[168:171], v144 offset:2048
	ds_read_b128 v[172:175], v144 offset:3072
	v_lshl_add_u64 v[144:145], s[26:27], 0, v[136:137]
	s_add_i32 m0, s10, 0xc000
	ds_read_b128 v[176:179], v147
	ds_read_b128 v[180:183], v147 offset:1024
	ds_read_b128 v[184:187], v147 offset:2048
	ds_read_b128 v[188:191], v147 offset:3072
	ds_read_b128 v[198:201], v147 offset:4096
	ds_read_b128 v[206:209], v147 offset:5120
	ds_read_b128 v[210:213], v147 offset:6144
	ds_read_b128 v[234:237], v147 offset:7168
	global_load_lds_dwordx4 v[144:145], off
	v_lshl_add_u64 v[144:145], s[26:27], 0, v[138:139]
	s_add_i32 m0, s10, 0xe000
	s_nop 0
	global_load_lds_dwordx4 v[144:145], off
	s_waitcnt vmcnt(8)
	s_waitcnt lgkmcnt(0)
	s_barrier
	s_waitcnt lgkmcnt(0)
	v_mfma_f32_16x16x32_bf16 v[126:129], v[140:143], v[176:179], v[126:129]
	v_mfma_f32_16x16x32_bf16 v[122:125], v[152:155], v[176:179], v[122:125]
	v_mfma_f32_16x16x32_bf16 v[108:111], v[140:143], v[184:187], v[108:111]
	v_mfma_f32_16x16x32_bf16 v[104:107], v[152:155], v[184:187], v[104:107]
	v_mfma_f32_16x16x32_bf16 v[92:95], v[140:143], v[198:201], v[92:95]
	v_mfma_f32_16x16x32_bf16 v[88:91], v[152:155], v[198:201], v[88:91]
	v_mfma_f32_16x16x32_bf16 v[76:79], v[140:143], v[210:213], v[76:79]
	v_mfma_f32_16x16x32_bf16 v[72:75], v[152:155], v[210:213], v[72:75]
	v_mfma_f32_16x16x32_bf16 v[126:129], v[148:151], v[180:183], v[126:129]
	v_mfma_f32_16x16x32_bf16 v[122:125], v[156:159], v[180:183], v[122:125]
	v_mfma_f32_16x16x32_bf16 v[108:111], v[148:151], v[188:191], v[108:111]
	v_mfma_f32_16x16x32_bf16 v[104:107], v[156:159], v[188:191], v[104:107]
	v_mfma_f32_16x16x32_bf16 v[92:95], v[148:151], v[206:209], v[92:95]
	v_mfma_f32_16x16x32_bf16 v[88:91], v[156:159], v[206:209], v[88:91]
	v_mfma_f32_16x16x32_bf16 v[76:79], v[148:151], v[234:237], v[76:79]
	v_mfma_f32_16x16x32_bf16 v[72:75], v[156:159], v[234:237], v[72:75]
	v_mfma_f32_16x16x32_bf16 v[118:121], v[160:163], v[176:179], v[118:121]
	v_mfma_f32_16x16x32_bf16 v[114:117], v[168:171], v[176:179], v[114:117]
	v_mfma_f32_16x16x32_bf16 v[100:103], v[160:163], v[184:187], v[100:103]
	v_mfma_f32_16x16x32_bf16 v[96:99], v[168:171], v[184:187], v[96:99]
	v_mfma_f32_16x16x32_bf16 v[84:87], v[160:163], v[198:201], v[84:87]
	v_mfma_f32_16x16x32_bf16 v[80:83], v[168:171], v[198:201], v[80:83]
	v_mfma_f32_16x16x32_bf16 v[68:71], v[160:163], v[210:213], v[68:71]
	v_mfma_f32_16x16x32_bf16 v[64:67], v[168:171], v[210:213], v[64:67]
	v_mfma_f32_16x16x32_bf16 v[118:121], v[164:167], v[180:183], v[118:121]
	v_mfma_f32_16x16x32_bf16 v[114:117], v[172:175], v[180:183], v[114:117]
	v_mfma_f32_16x16x32_bf16 v[100:103], v[164:167], v[188:191], v[100:103]
	v_mfma_f32_16x16x32_bf16 v[96:99], v[172:175], v[188:191], v[96:99]
	v_mfma_f32_16x16x32_bf16 v[84:87], v[164:167], v[206:209], v[84:87]
	v_mfma_f32_16x16x32_bf16 v[80:83], v[172:175], v[206:209], v[80:83]
	v_mfma_f32_16x16x32_bf16 v[68:71], v[164:167], v[234:237], v[68:71]
	v_mfma_f32_16x16x32_bf16 v[64:67], v[172:175], v[234:237], v[64:67]
	s_barrier
	s_add_i32 s26, s84, s9
	v_lshl_add_u64 v[144:145], s[62:63], 0, v[112:113]
	s_mov_b32 m0, s26
	ds_read_b128 v[176:179], v147 offset:16384
	ds_read_b128 v[180:183], v147 offset:17408
	ds_read_b128 v[184:187], v147 offset:18432
	ds_read_b128 v[188:191], v147 offset:19456
	ds_read_b128 v[198:201], v147 offset:20480
	ds_read_b128 v[206:209], v147 offset:21504
	ds_read_b128 v[210:213], v147 offset:22528
	ds_read_b128 v[234:237], v147 offset:23552
	global_load_lds_dwordx4 v[144:145], off
	s_add_i32 m0, s26, 0x2000
	s_add_u32 s26, s62, 0x58000
	v_lshl_add_u64 v[192:193], s[62:63], 0, v[134:135]
	s_addc_u32 s27, s63, 0
	s_add_i32 s84, s85, s9
	global_load_lds_dwordx4 v[192:193], off
	v_lshl_add_u64 v[238:239], s[26:27], 0, v[112:113]
	s_mov_b32 m0, s84
	v_lshl_add_u64 v[240:241], s[74:75], 0, v[132:133]
	global_load_lds_dwordx4 v[238:239], off
	v_lshl_add_u64 v[238:239], s[26:27], 0, v[134:135]
	s_add_i32 m0, s84, 0x2000
	s_nop 0
	global_load_lds_dwordx4 v[238:239], off
	s_waitcnt vmcnt(6)
	s_waitcnt lgkmcnt(0)
	s_barrier
	s_waitcnt lgkmcnt(0)
	v_mfma_f32_16x16x32_bf16 v[60:63], v[140:143], v[176:179], v[60:63]
	v_mfma_f32_16x16x32_bf16 v[56:59], v[152:155], v[176:179], v[56:59]
	v_mfma_f32_16x16x32_bf16 v[44:47], v[140:143], v[184:187], v[44:47]
	v_mfma_f32_16x16x32_bf16 v[40:43], v[152:155], v[184:187], v[40:43]
	v_mfma_f32_16x16x32_bf16 v[28:31], v[140:143], v[198:201], v[28:31]
	v_mfma_f32_16x16x32_bf16 v[24:27], v[152:155], v[198:201], v[24:27]
	v_mfma_f32_16x16x32_bf16 v[12:15], v[140:143], v[210:213], v[12:15]
	v_mfma_f32_16x16x32_bf16 v[8:11], v[152:155], v[210:213], v[8:11]
	v_mfma_f32_16x16x32_bf16 v[60:63], v[148:151], v[180:183], v[60:63]
	v_mfma_f32_16x16x32_bf16 v[56:59], v[156:159], v[180:183], v[56:59]
	v_mfma_f32_16x16x32_bf16 v[44:47], v[148:151], v[188:191], v[44:47]
	v_mfma_f32_16x16x32_bf16 v[40:43], v[156:159], v[188:191], v[40:43]
	v_mfma_f32_16x16x32_bf16 v[28:31], v[148:151], v[206:209], v[28:31]
	v_mfma_f32_16x16x32_bf16 v[24:27], v[156:159], v[206:209], v[24:27]
	v_mfma_f32_16x16x32_bf16 v[12:15], v[148:151], v[234:237], v[12:15]
	v_mfma_f32_16x16x32_bf16 v[8:11], v[156:159], v[234:237], v[8:11]
	v_mfma_f32_16x16x32_bf16 v[52:55], v[160:163], v[176:179], v[52:55]
	v_mfma_f32_16x16x32_bf16 v[48:51], v[168:171], v[176:179], v[48:51]
	v_mfma_f32_16x16x32_bf16 v[36:39], v[160:163], v[184:187], v[36:39]
	v_mfma_f32_16x16x32_bf16 v[32:35], v[168:171], v[184:187], v[32:35]
	v_mfma_f32_16x16x32_bf16 v[20:23], v[160:163], v[198:201], v[20:23]
	v_mfma_f32_16x16x32_bf16 v[16:19], v[168:171], v[198:201], v[16:19]
	v_mfma_f32_16x16x32_bf16 v[4:7], v[160:163], v[210:213], v[4:7]
	v_mfma_f32_16x16x32_bf16 v[0:3], v[168:171], v[210:213], v[0:3]
	v_mfma_f32_16x16x32_bf16 v[52:55], v[164:167], v[180:183], v[52:55]
	v_mfma_f32_16x16x32_bf16 v[48:51], v[172:175], v[180:183], v[48:51]
	v_mfma_f32_16x16x32_bf16 v[36:39], v[164:167], v[188:191], v[36:39]
	v_mfma_f32_16x16x32_bf16 v[32:35], v[172:175], v[188:191], v[32:35]
	v_mfma_f32_16x16x32_bf16 v[20:23], v[164:167], v[206:209], v[20:23]
	v_mfma_f32_16x16x32_bf16 v[16:19], v[172:175], v[206:209], v[16:19]
	v_mfma_f32_16x16x32_bf16 v[4:7], v[164:167], v[234:237], v[4:7]
	v_mfma_f32_16x16x32_bf16 v[0:3], v[172:175], v[234:237], v[0:3]
	s_barrier
	s_add_i32 s84, 0, 0x18000
	s_add_i32 s85, 0, 0x1c000
	v_add_u32_e32 v156, s84, v146
	v_add_u32_e32 v172, s85, v146
	ds_read_b128 v[140:143], v156
	ds_read_b128 v[148:151], v156 offset:1024
	ds_read_b128 v[152:155], v156 offset:2048
	ds_read_b128 v[156:159], v156 offset:3072
	ds_read_b128 v[160:163], v172
	ds_read_b128 v[164:167], v172 offset:1024
	ds_read_b128 v[168:171], v172 offset:2048
	ds_read_b128 v[172:175], v172 offset:3072
	v_lshl_add_u64 v[238:239], s[74:75], 0, v[130:131]
	s_mov_b32 m0, s10
	s_nop 0
	global_load_lds_dwordx4 v[238:239], off
	s_mov_b32 m0, s11
	s_nop 0
	global_load_lds_dwordx4 v[240:241], off
	s_add_u32 s26, s74, 0x160000
	s_addc_u32 s27, s75, 0
	s_mov_b32 m0, s24
	v_lshl_add_u64 v[242:243], s[26:27], 0, v[130:131]
	ds_read_b128 v[176:179], v147 offset:32768
	ds_read_b128 v[180:183], v147 offset:33792
	ds_read_b128 v[184:187], v147 offset:34816
	ds_read_b128 v[188:191], v147 offset:35840
	ds_read_b128 v[198:201], v147 offset:36864
	ds_read_b128 v[206:209], v147 offset:37888
	ds_read_b128 v[210:213], v147 offset:38912
	ds_read_b128 v[234:237], v147 offset:39936
	global_load_lds_dwordx4 v[242:243], off
	v_lshl_add_u64 v[242:243], s[26:27], 0, v[132:133]
	s_mov_b32 m0, s25
	s_nop 0
	global_load_lds_dwordx4 v[242:243], off
	s_waitcnt vmcnt(8)
	s_waitcnt lgkmcnt(0)
	s_barrier
	s_waitcnt lgkmcnt(0)
	v_mfma_f32_16x16x32_bf16 v[126:129], v[140:143], v[176:179], v[126:129]
	v_mfma_f32_16x16x32_bf16 v[122:125], v[152:155], v[176:179], v[122:125]
	v_mfma_f32_16x16x32_bf16 v[108:111], v[140:143], v[184:187], v[108:111]
	v_mfma_f32_16x16x32_bf16 v[104:107], v[152:155], v[184:187], v[104:107]
	v_mfma_f32_16x16x32_bf16 v[92:95], v[140:143], v[198:201], v[92:95]
	v_mfma_f32_16x16x32_bf16 v[88:91], v[152:155], v[198:201], v[88:91]
	v_mfma_f32_16x16x32_bf16 v[76:79], v[140:143], v[210:213], v[76:79]
	v_mfma_f32_16x16x32_bf16 v[72:75], v[152:155], v[210:213], v[72:75]
	v_mfma_f32_16x16x32_bf16 v[126:129], v[148:151], v[180:183], v[126:129]
	v_mfma_f32_16x16x32_bf16 v[122:125], v[156:159], v[180:183], v[122:125]
	v_mfma_f32_16x16x32_bf16 v[108:111], v[148:151], v[188:191], v[108:111]
	v_mfma_f32_16x16x32_bf16 v[104:107], v[156:159], v[188:191], v[104:107]
	v_mfma_f32_16x16x32_bf16 v[92:95], v[148:151], v[206:209], v[92:95]
	v_mfma_f32_16x16x32_bf16 v[88:91], v[156:159], v[206:209], v[88:91]
	v_mfma_f32_16x16x32_bf16 v[76:79], v[148:151], v[234:237], v[76:79]
	v_mfma_f32_16x16x32_bf16 v[72:75], v[156:159], v[234:237], v[72:75]
	v_mfma_f32_16x16x32_bf16 v[118:121], v[160:163], v[176:179], v[118:121]
	v_mfma_f32_16x16x32_bf16 v[114:117], v[168:171], v[176:179], v[114:117]
	v_mfma_f32_16x16x32_bf16 v[100:103], v[160:163], v[184:187], v[100:103]
	v_mfma_f32_16x16x32_bf16 v[96:99], v[168:171], v[184:187], v[96:99]
	v_mfma_f32_16x16x32_bf16 v[84:87], v[160:163], v[198:201], v[84:87]
	v_mfma_f32_16x16x32_bf16 v[80:83], v[168:171], v[198:201], v[80:83]
	v_mfma_f32_16x16x32_bf16 v[68:71], v[160:163], v[210:213], v[68:71]
	v_mfma_f32_16x16x32_bf16 v[64:67], v[168:171], v[210:213], v[64:67]
	v_mfma_f32_16x16x32_bf16 v[118:121], v[164:167], v[180:183], v[118:121]
	v_mfma_f32_16x16x32_bf16 v[114:117], v[172:175], v[180:183], v[114:117]
	v_mfma_f32_16x16x32_bf16 v[100:103], v[164:167], v[188:191], v[100:103]
	v_mfma_f32_16x16x32_bf16 v[96:99], v[172:175], v[188:191], v[96:99]
	v_mfma_f32_16x16x32_bf16 v[84:87], v[164:167], v[206:209], v[84:87]
	v_mfma_f32_16x16x32_bf16 v[80:83], v[172:175], v[206:209], v[80:83]
	v_mfma_f32_16x16x32_bf16 v[68:71], v[164:167], v[234:237], v[68:71]
	v_mfma_f32_16x16x32_bf16 v[64:67], v[172:175], v[234:237], v[64:67]
	s_barrier
	s_add_i32 s26, s84, s9
	v_lshl_add_u64 v[144:145], v[144:145], 0, s[48:49]
	s_mov_b32 m0, s26
	ds_read_b128 v[176:179], v147 offset:49152
	ds_read_b128 v[180:183], v147 offset:50176
	ds_read_b128 v[184:187], v147 offset:51200
	ds_read_b128 v[188:191], v147 offset:52224
	ds_read_b128 v[198:201], v147 offset:53248
	ds_read_b128 v[206:209], v147 offset:54272
	ds_read_b128 v[210:213], v147 offset:55296
	ds_read_b128 v[234:237], v147 offset:56320
	global_load_lds_dwordx4 v[144:145], off
	s_add_i32 m0, s26, 0x2000
	s_add_u32 s26, s62, 0x58080
	v_lshl_add_u64 v[144:145], v[192:193], 0, s[48:49]
	s_addc_u32 s27, s63, 0
	s_add_i32 s62, s85, s9
	global_load_lds_dwordx4 v[144:145], off
	v_lshl_add_u64 v[144:145], s[26:27], 0, v[112:113]
	s_mov_b32 m0, s62
	s_nop 0
	global_load_lds_dwordx4 v[144:145], off
	v_lshl_add_u64 v[144:145], s[26:27], 0, v[134:135]
	s_add_i32 m0, s62, 0x2000
	s_nop 0
	global_load_lds_dwordx4 v[144:145], off
	v_lshl_add_u64 v[144:145], v[238:239], 0, s[48:49]
	s_mov_b32 m0, s55
	s_nop 0
	global_load_lds_dwordx4 v[144:145], off
	v_lshl_add_u64 v[144:145], v[240:241], 0, s[48:49]
	s_mov_b32 m0, s56
	s_nop 0
	global_load_lds_dwordx4 v[144:145], off
	s_waitcnt vmcnt(8)
	s_waitcnt lgkmcnt(0)
	s_barrier
	s_waitcnt lgkmcnt(0)
	v_mfma_f32_16x16x32_bf16 v[60:63], v[140:143], v[176:179], v[60:63]
	v_mfma_f32_16x16x32_bf16 v[56:59], v[152:155], v[176:179], v[56:59]
	v_mfma_f32_16x16x32_bf16 v[44:47], v[140:143], v[184:187], v[44:47]
	v_mfma_f32_16x16x32_bf16 v[40:43], v[152:155], v[184:187], v[40:43]
	v_mfma_f32_16x16x32_bf16 v[28:31], v[140:143], v[198:201], v[28:31]
	v_mfma_f32_16x16x32_bf16 v[24:27], v[152:155], v[198:201], v[24:27]
	v_mfma_f32_16x16x32_bf16 v[12:15], v[140:143], v[210:213], v[12:15]
	v_mfma_f32_16x16x32_bf16 v[8:11], v[152:155], v[210:213], v[8:11]
	v_mfma_f32_16x16x32_bf16 v[60:63], v[148:151], v[180:183], v[60:63]
	v_mfma_f32_16x16x32_bf16 v[56:59], v[156:159], v[180:183], v[56:59]
	v_mfma_f32_16x16x32_bf16 v[44:47], v[148:151], v[188:191], v[44:47]
	v_mfma_f32_16x16x32_bf16 v[40:43], v[156:159], v[188:191], v[40:43]
	v_mfma_f32_16x16x32_bf16 v[28:31], v[148:151], v[206:209], v[28:31]
	v_mfma_f32_16x16x32_bf16 v[24:27], v[156:159], v[206:209], v[24:27]
	v_mfma_f32_16x16x32_bf16 v[12:15], v[148:151], v[234:237], v[12:15]
	v_mfma_f32_16x16x32_bf16 v[8:11], v[156:159], v[234:237], v[8:11]
	v_mfma_f32_16x16x32_bf16 v[52:55], v[160:163], v[176:179], v[52:55]
	v_mfma_f32_16x16x32_bf16 v[48:51], v[168:171], v[176:179], v[48:51]
	v_mfma_f32_16x16x32_bf16 v[36:39], v[160:163], v[184:187], v[36:39]
	v_mfma_f32_16x16x32_bf16 v[32:35], v[168:171], v[184:187], v[32:35]
	v_mfma_f32_16x16x32_bf16 v[20:23], v[160:163], v[198:201], v[20:23]
	v_mfma_f32_16x16x32_bf16 v[16:19], v[168:171], v[198:201], v[16:19]
	v_mfma_f32_16x16x32_bf16 v[4:7], v[160:163], v[210:213], v[4:7]
	v_mfma_f32_16x16x32_bf16 v[0:3], v[168:171], v[210:213], v[0:3]
	v_mfma_f32_16x16x32_bf16 v[52:55], v[164:167], v[180:183], v[52:55]
	v_mfma_f32_16x16x32_bf16 v[48:51], v[172:175], v[180:183], v[48:51]
	v_mfma_f32_16x16x32_bf16 v[36:39], v[164:167], v[188:191], v[36:39]
	v_mfma_f32_16x16x32_bf16 v[32:35], v[172:175], v[188:191], v[32:35]
	v_mfma_f32_16x16x32_bf16 v[20:23], v[164:167], v[206:209], v[20:23]
	v_mfma_f32_16x16x32_bf16 v[16:19], v[172:175], v[206:209], v[16:19]
	v_mfma_f32_16x16x32_bf16 v[4:7], v[164:167], v[234:237], v[4:7]
	v_mfma_f32_16x16x32_bf16 v[0:3], v[172:175], v[234:237], v[0:3]
	s_barrier
	s_add_i32 s83, s83, 2
	s_add_u32 s81, s81, 0x100
	s_addc_u32 s82, s82, 0
	s_cmpk_gt_u32 s83, 0x55
	s_mov_b64 s[26:27], s[60:61]
	s_cbranch_scc0 .LBB1_1254
	s_and_b64 vcc, exec, s[16:17]
	s_cbranch_vccz .LBB1_1257
	s_barrier
